# diff-attn loop: V rows stored un-permuted so P needs no permlane32 swaps; DMA addresses formed on SALU (saddr form); K LDS swizzle over row&15; out0 epilogue loads hoisted above stores
# speedup vs baseline: 1.0915x; 1.0114x over previous
.LBB0_316:
	s_lshl_b32 s4, s63, 9
	v_mov_b32 v16, v144
	s_and_b32 s40, s4, 0x2000
	v_readfirstlane_b32 s35, v16
	s_lshl_b32 s4, s18, 7
	s_ashr_i32 s34, s35, 7
	s_and_b32 s4, s4, 0x1f80
	s_or_b32 s4, s4, s40
	s_lshl_b32 s18, s34, 5
	v_and_b32_e32 v136, 31, v16
	s_add_i32 s18, s18, s4
	v_or_b32_e32 v0, s18, v136
	v_ashrrev_i32_e32 v1, 31, v0
	s_lshl_b32 s4, s62, 6
	s_ashr_i32 s42, s35, 6
	v_lshlrev_b64 v[0:1], 13, v[0:1]
	s_and_b32 s4, s4, 0x380
	s_and_b32 s19, s42, 1
	v_lshl_add_u64 v[0:1], s[0:1], 0, v[0:1]
	s_lshl_b32 s6, s4, 1
	s_mov_b32 s7, s17
	v_lshl_add_u64 v[0:1], v[0:1], 0, s[6:7]
	s_lshl_b32 s4, s19, 7
	s_mov_b32 s5, s17
	s_lshl_b32 s44, s19, 6
	v_lshl_add_u64 v[0:1], v[0:1], 0, s[4:5]
	s_lshl_b32 s5, s40, 13
	s_add_u32 s5, s0, s5
	s_addc_u32 s7, s1, 0
	s_add_u32 s40, s5, s6
	s_addc_u32 s41, s7, 0
	s_lshl_b32 s7, s34, 3
	v_bfe_u32 v6, v16, 2, 3
	v_or_b32_e32 v18, s7, v6
	v_lshrrev_b32_e32 v6, 1, v16
	s_lshl_b32 s7, s34, 2
	s_lshl_b32 s5, s42, 2
	v_bfe_u32 v17, v16, 4, 2
	v_mov_b32_e32 v20, 0
	s_mov_b32 s45, 0
	v_or_b32_e32 v2, s5, v17
	v_and_b32_e32 v3, 15, v16
	v_or3_b32 v6, v18, v20, s45
	v_bitop3_b32 v4, v2, v3, 15 bitop3:0x6c
	v_ashrrev_i32_e32 v3, 31, v2
	v_ashrrev_i32_e32 v7, 31, v6
	v_and_b32_e32 v19, 32, v16
	v_lshlrev_b64 v[2:3], 13, v[2:3]
	v_lshlrev_b64 v[6:7], 13, v[6:7]
	v_or_b32_e32 v8, s44, v19
	v_lshl_add_u64 v[2:3], s[40:41], 0, v[2:3]
	v_lshlrev_b32_e32 v128, 4, v4
	v_lshl_add_u64 v[6:7], s[40:41], 0, v[6:7]
	v_lshlrev_b32_e32 v8, 1, v8
	v_mov_b32_e32 v9, v129
	s_lshl_b32 s7, s42, 10
	v_lshl_add_u64 v[2:3], v[2:3], 0, v[128:129]
	v_lshl_add_u64 v[6:7], v[6:7], 0, v[8:9]
	v_lshlrev_b32_e32 v8, 4, v16
	s_add_i32 s40, s38, s7
	v_lshl_add_u64 v[4:5], v[2:3], 0, s[48:49]
	v_and_b32_e32 v8, 48, v8
	s_mov_b32 m0, s40
	s_add_i32 s42, s7, 0x2000
	s_barrier
	v_lshl_add_u64 v[6:7], v[6:7], 0, v[8:9]
	global_load_lds_dwordx4 v[4:5], off
	v_lshl_add_u64 v[4:5], v[2:3], 0, s[52:53]
	s_add_i32 m0, s38, s42
	s_add_i32 s41, s7, 0
	v_lshl_add_u64 v[8:9], v[6:7], 0, s[50:51]
	global_load_lds_dwordx4 v[4:5], off
	s_mov_b32 m0, s41
	v_lshl_add_u64 v[4:5], v[6:7], 0, s[54:55]
	global_load_lds_dwordx4 v[8:9], off
	s_add_i32 m0, s41, 0x2000
	s_mov_b64 s[46:47], 0x80800
	global_load_lds_dwordx4 v[4:5], off
	v_lshl_add_u64 v[4:5], v[2:3], 0, s[46:47]
	s_add_i32 m0, s64, s7
	s_mov_b64 s[46:47], 0xc0800
	global_load_lds_dwordx4 v[4:5], off
	v_lshl_add_u64 v[4:5], v[2:3], 0, s[46:47]
	s_add_i32 m0, s64, s42
	s_mov_b64 s[46:47], 0x81000
	global_load_lds_dwordx4 v[4:5], off
	v_lshl_add_u64 v[4:5], v[6:7], 0, s[46:47]
	s_add_i32 m0, s41, 0x4000
	s_mov_b64 s[46:47], 0xc1000
	global_load_lds_dwordx4 v[4:5], off
	v_lshl_add_u64 v[4:5], v[6:7], 0, s[46:47]
	s_add_i32 m0, s41, 0x6000
	s_mov_b64 s[46:47], 0x100800
	global_load_lds_dwordx4 v[4:5], off
	v_lshl_add_u64 v[4:5], v[2:3], 0, s[46:47]
	s_add_i32 m0, s39, s7
	s_mov_b64 s[46:47], 0x140800
	global_load_lds_dwordx4 v[4:5], off
	v_lshl_add_u64 v[4:5], v[2:3], 0, s[46:47]
	s_add_i32 m0, s39, s42
	s_mov_b64 s[46:47], 0x101000
	global_load_lds_dwordx4 v[4:5], off
	v_lshl_add_u64 v[4:5], v[6:7], 0, s[46:47]
	s_add_i32 m0, s41, 0x8000
	s_mov_b64 s[46:47], 0x141000
	global_load_lds_dwordx4 v[4:5], off
	v_lshl_add_u64 v[4:5], v[6:7], 0, s[46:47]
	s_add_i32 m0, s41, 0xa000
	v_bfe_u32 v137, v16, 5, 1
	global_load_lds_dwordx4 v[4:5], off
	v_lshl_add_u64 v[4:5], v[2:3], 0, s[76:77]
	s_add_i32 m0, s56, s7
	v_lshl_add_u64 v[2:3], v[2:3], 0, s[78:79]
	global_load_lds_dwordx4 v[4:5], off
	s_add_i32 m0, s56, s42
	v_lshlrev_b32_e32 v130, 4, v137
	global_load_lds_dwordx4 v[2:3], off
	v_lshl_add_u64 v[2:3], v[6:7], 0, s[80:81]
	s_add_i32 m0, s41, 0xc000
	v_mov_b32_e32 v131, v129
	global_load_lds_dwordx4 v[2:3], off
	v_lshl_add_u64 v[2:3], v[6:7], 0, s[82:83]
	s_add_i32 m0, s41, 0xe000
	v_lshl_add_u64 v[0:1], v[0:1], 0, v[130:131]
	global_load_lds_dwordx4 v[2:3], off
	global_load_dwordx4 v[124:127], v[0:1], off
	global_load_dwordx4 v[120:123], v[0:1], off offset:32
	global_load_dwordx4 v[116:119], v[0:1], off offset:64
	global_load_dwordx4 v[112:115], v[0:1], off offset:96
	s_cmpk_lt_i32 s35, 0x100
	s_cbranch_scc1 .LBB0_318
	s_setprio 1
.LBB0_318:
	v_and_b32_e32 v131, 63, v16
	v_lshlrev_b32_e32 v0, 4, v136
	v_lshlrev_b32_e32 v30, 8, v136
	v_and_b32_e32 v31, 0xf0, v0
	v_or_b32_e32 v21, s4, v130
	v_bitop3_b32 v149, v21, v30, v31 bitop3:0xde
	v_or_b32_e32 v22, 32, v21
	v_bitop3_b32 v148, v22, v30, v31 bitop3:0xde
	v_or_b32_e32 v22, 64, v21
	v_bitop3_b32 v143, v22, v30, v31 bitop3:0xde
	v_or_b32_e32 v22, 0x60, v21
	v_bitop3_b32 v141, v22, v30, v31 bitop3:0xde
	v_add_u32_e32 v149, s38, v149
	v_add_u32_e32 v148, s38, v148
	v_add_u32_e32 v143, s38, v143
	v_add_u32_e32 v141, s38, v141
	v_lshlrev_b32_e32 v34, 4, v131
	v_lshlrev_b32_e32 v33, 3, v131
	v_and_b32_e32 v22, 0xc0, v34
	v_and_or_b32 v34, v33, 24, v22
	v_lshlrev_b32_e32 v26, 1, v131
	v_and_b32_e32 v30, 32, v26
	v_and_b32_e32 v33, 0x100, v33
	v_or3_b32 v140, v34, v30, v33
	v_mov_b32_e32 v151, v140
	v_add3_u32 v0, v18, v20, s45
	v_ashrrev_i32_e32 v1, 31, v0
	v_lshlrev_b64 v[0:1], 13, v[0:1]
	v_and_b32_e32 v2, 3, v16
	v_lshl_add_u64 v[0:1], s[10:11], 0, v[0:1]
	v_lshlrev_b32_e32 v2, 4, v2
	v_mov_b32_e32 v3, v129
	v_lshl_add_u64 v[0:1], v[0:1], 0, v[2:3]
	v_add_lshl_u32 v2, s44, v19, 1
	v_lshl_add_u64 v[0:1], v[0:1], 0, v[2:3]
	v_lshl_add_u64 v[132:133], s[28:29], 0, v[0:1]
	v_add_u32_e32 v0, s5, v17
	v_ashrrev_i32_e32 v1, 31, v0
	v_lshlrev_b64 v[0:1], 13, v[0:1]
	v_lshl_add_u64 v[0:1], s[10:11], 0, v[0:1]
	v_lshl_add_u64 v[0:1], v[0:1], 0, v[128:129]
	v_lshl_add_u64 v[134:135], s[28:29], 0, v[0:1]
	v_lshl_add_u64 v[132:133], v[132:133], 0, s[16:17]
	v_lshl_add_u64 v[134:135], v[134:135], 0, s[16:17]
	v_add3_u32 v0, v18, v20, s45
	v_lshlrev_b32_e32 v0, 13, v0
	v_and_b32_e32 v2, 3, v16
	v_lshl_add_u32 v0, v2, 4, v0
	v_add_lshl_u32 v2, s44, v19, 1
	v_add_u32_e32 v150, v0, v2
	v_add_u32_e32 v0, s5, v17
	v_lshl_add_u32 v142, v0, 13, v128
	s_add_u32 s72, s28, s10
	s_addc_u32 s73, s29, s11
	s_add_u32 s72, s72, s16
	s_addc_u32 s73, s73, s17
	s_mov_b32 s46, s72
	s_mov_b32 s47, s73
	s_mov_b32 s62, 0
	s_add_i32 s71, s41, 0x2000
	s_movk_i32 s70, 31
	v_mov_b32_e32 v0, 0
	v_mov_b32_e32 v1, 0
	v_mov_b32_e32 v2, 0
	v_mov_b32_e32 v3, 0
	v_mov_b32_e32 v4, 0
	v_mov_b32_e32 v5, 0
	v_mov_b32_e32 v6, 0
	v_mov_b32_e32 v7, 0
	v_mov_b32_e32 v8, 0
	v_mov_b32_e32 v9, 0
	v_mov_b32_e32 v10, 0
	v_mov_b32_e32 v11, 0
	v_mov_b32_e32 v12, 0
	v_mov_b32_e32 v13, 0
	v_mov_b32_e32 v14, 0
	v_mov_b32_e32 v15, 0
	v_mov_b32_e32 v16, 0
	v_mov_b32_e32 v17, 0
	v_mov_b32_e32 v18, 0
	v_mov_b32_e32 v19, 0
	v_mov_b32_e32 v20, 0
	v_mov_b32_e32 v21, 0
	v_mov_b32_e32 v22, 0
	v_mov_b32_e32 v23, 0
	v_mov_b32_e32 v24, 0
	v_mov_b32_e32 v25, 0
	v_mov_b32_e32 v26, 0
	v_mov_b32_e32 v27, 0
	v_mov_b32_e32 v28, 0
	v_mov_b32_e32 v29, 0
	v_mov_b32_e32 v30, 0
	v_mov_b32_e32 v31, 0
	v_mov_b32_e32 v32, 0
	v_mov_b32_e32 v33, 0
	v_mov_b32_e32 v34, 0
	v_mov_b32_e32 v35, 0
	v_mov_b32_e32 v36, 0
	v_mov_b32_e32 v37, 0
	v_mov_b32_e32 v38, 0
	v_mov_b32_e32 v39, 0
	v_mov_b32_e32 v40, 0
	v_mov_b32_e32 v41, 0
	v_mov_b32_e32 v42, 0
	v_mov_b32_e32 v43, 0
	v_mov_b32_e32 v44, 0
	v_mov_b32_e32 v45, 0
	v_mov_b32_e32 v46, 0
	v_mov_b32_e32 v47, 0
	v_mov_b32_e32 v48, 0
	v_mov_b32_e32 v49, 0
	v_mov_b32_e32 v50, 0
	v_mov_b32_e32 v51, 0
	v_mov_b32_e32 v52, 0
	v_mov_b32_e32 v53, 0
	v_mov_b32_e32 v54, 0
	v_mov_b32_e32 v55, 0
	v_mov_b32_e32 v56, 0
	v_mov_b32_e32 v57, 0
	v_mov_b32_e32 v58, 0
	v_mov_b32_e32 v59, 0
	v_mov_b32_e32 v60, 0
	v_mov_b32_e32 v61, 0
	v_mov_b32_e32 v62, 0
	v_mov_b32_e32 v63, 0
	v_mov_b32_e32 v234, 0
	v_mov_b32_e32 v235, 0
	s_waitcnt vmcnt(0)
	s_barrier
	ds_read_b128 v[194:197], v149 offset:0
	ds_read_b128 v[198:201], v148 offset:0
	ds_read_b128 v[202:205], v143 offset:0
	ds_read_b128 v[206:209], v141 offset:0
	ds_read_b128 v[210:213], v149 offset:8192
	ds_read_b128 v[214:217], v148 offset:8192
	ds_read_b128 v[218:221], v143 offset:8192
	ds_read_b128 v[222:225], v141 offset:8192
	s_waitcnt lgkmcnt(7)
	v_mfma_f32_32x32x16_bf16 v[64:79], v[194:197], v[124:127], 0
	s_waitcnt lgkmcnt(6)
	v_mfma_f32_32x32x16_bf16 v[64:79], v[198:201], v[120:123], v[64:79]
	s_waitcnt lgkmcnt(5)
	v_mfma_f32_32x32x16_bf16 v[64:79], v[202:205], v[116:119], v[64:79]
	s_waitcnt lgkmcnt(4)
	v_mfma_f32_32x32x16_bf16 v[64:79], v[206:209], v[112:115], v[64:79]
	s_waitcnt lgkmcnt(3)
	v_mfma_f32_32x32x16_bf16 v[80:95], v[210:213], v[124:127], 0
	s_waitcnt lgkmcnt(2)
	v_mfma_f32_32x32x16_bf16 v[80:95], v[214:217], v[120:123], v[80:95]
	s_waitcnt lgkmcnt(1)
	v_mfma_f32_32x32x16_bf16 v[80:95], v[218:221], v[116:119], v[80:95]
	s_waitcnt lgkmcnt(0)
	v_mfma_f32_32x32x16_bf16 v[80:95], v[222:225], v[112:115], v[80:95]
	s_nop 3
	v_exp_f32_e32 v64, v64
	v_exp_f32_e32 v65, v65
	ds_read_b128 v[194:197], v149 offset:16384
	v_exp_f32_e32 v66, v66
	v_exp_f32_e32 v67, v67
	v_add_f32_e32 v234, v234, v64
	ds_read_b128 v[198:201], v148 offset:16384
	v_exp_f32_e32 v68, v68
	v_exp_f32_e32 v69, v69
	v_add_f32_e32 v235, v235, v65
	v_add_f32_e32 v234, v234, v66
	ds_read_b128 v[202:205], v143 offset:16384
	v_exp_f32_e32 v70, v70
	v_exp_f32_e32 v71, v71
	v_add_f32_e32 v235, v235, v67
	v_add_f32_e32 v234, v234, v68
	ds_read_b128 v[206:209], v141 offset:16384
	v_add_f32_e32 v235, v235, v69
	v_add_f32_e32 v234, v234, v70
	v_add_f32_e32 v235, v235, v71
	v_cvt_pk_bf16_f32 v178, v64, v65
	v_cvt_pk_bf16_f32 v180, v68, v69
	ds_read_b128 v[210:213], v149 offset:24576
	v_cvt_pk_bf16_f32 v179, v66, v67
	v_cvt_pk_bf16_f32 v181, v70, v71
	ds_read_b128 v[214:217], v148 offset:24576
.Lda_loop:
	s_waitcnt lgkmcnt(5)
	v_mfma_f32_32x32x16_bf16 v[96:111], v[194:197], v[124:127], 0
	v_exp_f32_e32 v72, v72
	v_exp_f32_e32 v73, v73
	ds_read_b128 v[218:221], v143 offset:24576
	s_waitcnt lgkmcnt(5)
	v_mfma_f32_32x32x16_bf16 v[96:111], v[198:201], v[120:123], v[96:111]
	v_exp_f32_e32 v74, v74
	v_exp_f32_e32 v75, v75
	v_add_f32_e32 v234, v234, v72
	ds_read_b128 v[222:225], v141 offset:24576
	ds_read_b64_tr_b16 v[226:227], v151 offset:0
	ds_read_b64_tr_b16 v[228:229], v151 offset:2048
	s_waitcnt lgkmcnt(7)
	v_mfma_f32_32x32x16_bf16 v[96:111], v[202:205], v[116:119], v[96:111]
	v_exp_f32_e32 v76, v76
	v_exp_f32_e32 v77, v77
	v_add_f32_e32 v235, v235, v73
	v_add_f32_e32 v234, v234, v74
	ds_read_b64_tr_b16 v[230:231], v151 offset:512
	ds_read_b64_tr_b16 v[232:233], v151 offset:2560
	s_waitcnt lgkmcnt(8)
	v_mfma_f32_32x32x16_bf16 v[96:111], v[206:209], v[112:115], v[96:111]
	v_exp_f32_e32 v78, v78
	v_exp_f32_e32 v79, v79
	v_add_f32_e32 v235, v235, v75
	v_add_f32_e32 v234, v234, v76
	ds_read_b64_tr_b16 v[238:239], v151 offset:1024
	ds_read_b64_tr_b16 v[240:241], v151 offset:3072
	s_waitcnt lgkmcnt(9)
	v_mfma_f32_32x32x16_bf16 v[162:177], v[210:213], v[124:127], 0
	v_add_f32_e32 v235, v235, v77
	v_add_f32_e32 v234, v234, v78
	v_add_f32_e32 v235, v235, v79
	v_cvt_pk_bf16_f32 v182, v72, v73
	v_cvt_pk_bf16_f32 v184, v76, v77
	ds_read_b64_tr_b16 v[242:243], v151 offset:1536
	ds_read_b64_tr_b16 v[244:245], v151 offset:3584
	s_waitcnt lgkmcnt(10)
	v_mfma_f32_32x32x16_bf16 v[162:177], v[214:217], v[120:123], v[162:177]
	v_cvt_pk_bf16_f32 v183, v74, v75
	v_cvt_pk_bf16_f32 v185, v78, v79
	ds_read_b64_tr_b16 v[246:247], v151 offset:4096
	ds_read_b64_tr_b16 v[248:249], v151 offset:6144
	s_waitcnt lgkmcnt(11)
	v_mfma_f32_32x32x16_bf16 v[162:177], v[218:221], v[116:119], v[162:177]
	v_exp_f32_e32 v80, v80
	v_exp_f32_e32 v81, v81
	ds_read_b64_tr_b16 v[250:251], v151 offset:4608
	ds_read_b64_tr_b16 v[252:253], v151 offset:6656
	s_waitcnt lgkmcnt(12)
	v_mfma_f32_32x32x16_bf16 v[162:177], v[222:225], v[112:115], v[162:177]
	v_exp_f32_e32 v82, v82
	v_exp_f32_e32 v83, v83
	v_add_f32_e32 v234, v234, v80
	ds_read_b64_tr_b16 v[152:153], v151 offset:5120
	ds_read_b64_tr_b16 v[154:155], v151 offset:7168
	s_waitcnt lgkmcnt(12)
	v_mfma_f32_32x32x16_bf16 v[48:63], v[178:181], v[226:229], v[48:63]
	v_exp_f32_e32 v84, v84
	v_exp_f32_e32 v85, v85
	v_add_f32_e32 v235, v235, v81
	v_add_f32_e32 v234, v234, v82
	ds_read_b64_tr_b16 v[226:227], v151 offset:5632
	ds_read_b64_tr_b16 v[228:229], v151 offset:7680
	s_waitcnt lgkmcnt(12)
	v_mfma_f32_32x32x16_bf16 v[32:47], v[178:181], v[230:233], v[32:47]
	v_exp_f32_e32 v86, v86
	v_exp_f32_e32 v87, v87
	v_add_f32_e32 v235, v235, v83
	v_add_f32_e32 v234, v234, v84
	ds_read_b64_tr_b16 v[230:231], v151 offset:8192
	ds_read_b64_tr_b16 v[232:233], v151 offset:10240
	s_waitcnt lgkmcnt(12)
	v_mfma_f32_32x32x16_bf16 v[16:31], v[178:181], v[238:241], v[16:31]
	v_add_f32_e32 v235, v235, v85
	v_add_f32_e32 v234, v234, v86
	v_add_f32_e32 v235, v235, v87
	v_cvt_pk_bf16_f32 v186, v80, v81
	v_cvt_pk_bf16_f32 v188, v84, v85
	ds_read_b64_tr_b16 v[238:239], v151 offset:8704
	ds_read_b64_tr_b16 v[240:241], v151 offset:10752
	s_waitcnt lgkmcnt(12)
	v_mfma_f32_32x32x16_bf16 v[0:15], v[178:181], v[242:245], v[0:15]
	v_cvt_pk_bf16_f32 v187, v82, v83
	v_cvt_pk_bf16_f32 v189, v86, v87
	ds_read_b64_tr_b16 v[242:243], v151 offset:9216
	ds_read_b64_tr_b16 v[244:245], v151 offset:11264
	s_waitcnt lgkmcnt(12)
	v_mfma_f32_32x32x16_bf16 v[48:63], v[182:185], v[246:249], v[48:63]
	v_exp_f32_e32 v88, v88
	v_exp_f32_e32 v89, v89
	ds_read_b64_tr_b16 v[246:247], v151 offset:9728
	ds_read_b64_tr_b16 v[248:249], v151 offset:11776
	s_waitcnt lgkmcnt(12)
	v_mfma_f32_32x32x16_bf16 v[32:47], v[182:185], v[250:253], v[32:47]
	v_exp_f32_e32 v90, v90
	v_exp_f32_e32 v91, v91
	v_add_f32_e32 v234, v234, v88
	ds_read_b64_tr_b16 v[250:251], v151 offset:12288
	ds_read_b64_tr_b16 v[252:253], v151 offset:14336
	s_waitcnt lgkmcnt(12)
	v_mfma_f32_32x32x16_bf16 v[16:31], v[182:185], v[152:155], v[16:31]
	v_exp_f32_e32 v92, v92
	v_exp_f32_e32 v93, v93
	v_add_f32_e32 v235, v235, v89
	v_add_f32_e32 v234, v234, v90
	ds_read_b64_tr_b16 v[152:153], v151 offset:12800
	ds_read_b64_tr_b16 v[154:155], v151 offset:14848
	s_waitcnt lgkmcnt(12)
	v_mfma_f32_32x32x16_bf16 v[0:15], v[182:185], v[226:229], v[0:15]
	v_exp_f32_e32 v94, v94
	v_exp_f32_e32 v95, v95
	v_add_f32_e32 v235, v235, v91
	v_add_f32_e32 v234, v234, v92
	ds_read_b64_tr_b16 v[226:227], v151 offset:13312
	ds_read_b64_tr_b16 v[228:229], v151 offset:15360
	s_waitcnt lgkmcnt(12)
	v_mfma_f32_32x32x16_bf16 v[48:63], v[186:189], v[230:233], v[48:63]
	v_add_f32_e32 v235, v235, v93
	v_add_f32_e32 v234, v234, v94
	v_add_f32_e32 v235, v235, v95
	v_cvt_pk_bf16_f32 v190, v88, v89
	v_cvt_pk_bf16_f32 v192, v92, v93
	ds_read_b64_tr_b16 v[230:231], v151 offset:13824
	ds_read_b64_tr_b16 v[232:233], v151 offset:15872
	s_waitcnt lgkmcnt(12)
	v_mfma_f32_32x32x16_bf16 v[32:47], v[186:189], v[238:241], v[32:47]
	s_waitcnt vmcnt(0)
	s_barrier
	s_add_i32 s63, s62, 0xc000
	s_cmp_ge_u32 s63, 0x14000
	s_cselect_b32 s69, 0x14000, 0
	s_sub_i32 s63, s63, s69
	s_add_i32 s68, s62, 0x10000
	s_cmp_ge_u32 s68, 0x14000
	s_cselect_b32 s69, 0x14000, 0
	s_sub_i32 s68, s68, s69
	s_add_i32 s62, s62, 0x4000
	s_cmp_ge_u32 s62, 0x14000
	s_cselect_b32 s69, 0x14000, 0
	s_sub_i32 s62, s62, s69
	v_add_u32_e32 v151, s62, v140
	v_cvt_pk_bf16_f32 v191, v90, v91
	v_cvt_pk_bf16_f32 v193, v94, v95
	s_add_i32 m0, s41, s63
	s_add_u32 s42, s46, 0x5d81000
	s_addc_u32 s43, s47, 0
	global_load_lds_dwordx4 v150, s[42:43]
	s_waitcnt lgkmcnt(10)
	v_mfma_f32_32x32x16_bf16 v[16:31], v[186:189], v[242:245], v[16:31]
	v_exp_f32_e32 v96, v96
	v_exp_f32_e32 v97, v97
	ds_read_b128 v[194:197], v149 offset:32768
	s_add_i32 m0, s71, s63
	s_add_u32 s42, s46, 0x5dc1000
	s_addc_u32 s43, s47, 0
	global_load_lds_dwordx4 v150, s[42:43]
	s_waitcnt lgkmcnt(9)
	v_mfma_f32_32x32x16_bf16 v[0:15], v[186:189], v[246:249], v[0:15]
	v_exp_f32_e32 v98, v98
	v_exp_f32_e32 v99, v99
	v_add_f32_e32 v234, v234, v96
	ds_read_b128 v[198:201], v148 offset:32768
	s_add_i32 m0, s40, 0x0
	s_add_u32 s42, s72, 0x5e00800
	s_addc_u32 s43, s73, 0
	global_load_lds_dwordx4 v142, s[42:43]
	s_waitcnt lgkmcnt(8)
	v_mfma_f32_32x32x16_bf16 v[48:63], v[190:193], v[250:253], v[48:63]
	v_exp_f32_e32 v100, v100
	v_exp_f32_e32 v101, v101
	v_add_f32_e32 v235, v235, v97
	v_add_f32_e32 v234, v234, v98
	ds_read_b128 v[202:205], v143 offset:32768
	s_add_i32 m0, s40, 0x2000
	s_add_u32 s42, s72, 0x5e40800
	s_addc_u32 s43, s73, 0
	global_load_lds_dwordx4 v142, s[42:43]
	s_waitcnt lgkmcnt(7)
	v_mfma_f32_32x32x16_bf16 v[32:47], v[190:193], v[152:155], v[32:47]
	v_exp_f32_e32 v102, v102
	v_exp_f32_e32 v103, v103
	v_add_f32_e32 v235, v235, v99
	v_add_f32_e32 v234, v234, v100
	ds_read_b128 v[206:209], v141 offset:32768
	s_add_i32 m0, s41, s68
	s_add_u32 s42, s46, 0x5e01000
	s_addc_u32 s43, s47, 0
	global_load_lds_dwordx4 v150, s[42:43]
	s_waitcnt lgkmcnt(6)
	v_mfma_f32_32x32x16_bf16 v[16:31], v[190:193], v[226:229], v[16:31]
	v_add_f32_e32 v235, v235, v101
	v_add_f32_e32 v234, v234, v102
	v_add_f32_e32 v235, v235, v103
	v_cvt_pk_bf16_f32 v178, v96, v97
	v_cvt_pk_bf16_f32 v180, v100, v101
	ds_read_b128 v[210:213], v149 offset:40960
	s_add_i32 m0, s71, s68
	s_add_u32 s42, s46, 0x5e41000
	s_addc_u32 s43, s47, 0
	global_load_lds_dwordx4 v150, s[42:43]
	s_waitcnt lgkmcnt(5)
	v_mfma_f32_32x32x16_bf16 v[0:15], v[190:193], v[230:233], v[0:15]
	v_cvt_pk_bf16_f32 v179, v98, v99
	v_cvt_pk_bf16_f32 v181, v102, v103
	ds_read_b128 v[214:217], v148 offset:40960
	s_add_i32 m0, s40, 0x4000
	s_add_u32 s42, s72, 0x5e80800
	s_addc_u32 s43, s73, 0
	global_load_lds_dwordx4 v142, s[42:43]
	s_add_i32 m0, s40, 0x6000
	s_add_u32 s42, s72, 0x5ec0800
	s_addc_u32 s43, s73, 0
	global_load_lds_dwordx4 v142, s[42:43]
	s_add_u32 s72, s72, 0x100000
	s_addc_u32 s73, s73, 0
	s_add_u32 s46, s46, 0x100000
	s_addc_u32 s47, s47, 0
	s_waitcnt lgkmcnt(5)
	v_mfma_f32_32x32x16_bf16 v[64:79], v[194:197], v[124:127], 0
	v_exp_f32_e32 v104, v104
	v_exp_f32_e32 v105, v105
	ds_read_b128 v[218:221], v143 offset:40960
	s_waitcnt lgkmcnt(5)
	v_mfma_f32_32x32x16_bf16 v[64:79], v[198:201], v[120:123], v[64:79]
	v_exp_f32_e32 v106, v106
	v_exp_f32_e32 v107, v107
	v_add_f32_e32 v234, v234, v104
	ds_read_b128 v[222:225], v141 offset:40960
	ds_read_b64_tr_b16 v[226:227], v151 offset:0
	ds_read_b64_tr_b16 v[228:229], v151 offset:2048
	s_waitcnt lgkmcnt(7)
	v_mfma_f32_32x32x16_bf16 v[64:79], v[202:205], v[116:119], v[64:79]
	v_exp_f32_e32 v108, v108
	v_exp_f32_e32 v109, v109
	v_add_f32_e32 v235, v235, v105
	v_add_f32_e32 v234, v234, v106
	ds_read_b64_tr_b16 v[230:231], v151 offset:512
	ds_read_b64_tr_b16 v[232:233], v151 offset:2560
	s_waitcnt lgkmcnt(8)
	v_mfma_f32_32x32x16_bf16 v[64:79], v[206:209], v[112:115], v[64:79]
	v_exp_f32_e32 v110, v110
	v_exp_f32_e32 v111, v111
	v_add_f32_e32 v235, v235, v107
	v_add_f32_e32 v234, v234, v108
	ds_read_b64_tr_b16 v[238:239], v151 offset:1024
	ds_read_b64_tr_b16 v[240:241], v151 offset:3072
	s_waitcnt lgkmcnt(9)
	v_mfma_f32_32x32x16_bf16 v[80:95], v[210:213], v[124:127], 0
	v_add_f32_e32 v235, v235, v109
	v_add_f32_e32 v234, v234, v110
	v_add_f32_e32 v235, v235, v111
	v_cvt_pk_bf16_f32 v182, v104, v105
	v_cvt_pk_bf16_f32 v184, v108, v109
	ds_read_b64_tr_b16 v[242:243], v151 offset:1536
	ds_read_b64_tr_b16 v[244:245], v151 offset:3584
	s_waitcnt lgkmcnt(10)
	v_mfma_f32_32x32x16_bf16 v[80:95], v[214:217], v[120:123], v[80:95]
	v_cvt_pk_bf16_f32 v183, v106, v107
	v_cvt_pk_bf16_f32 v185, v110, v111
	ds_read_b64_tr_b16 v[246:247], v151 offset:4096
	ds_read_b64_tr_b16 v[248:249], v151 offset:6144
	s_waitcnt lgkmcnt(11)
	v_mfma_f32_32x32x16_bf16 v[80:95], v[218:221], v[116:119], v[80:95]
	v_exp_f32_e32 v162, v162
	v_exp_f32_e32 v163, v163
	ds_read_b64_tr_b16 v[250:251], v151 offset:4608
	ds_read_b64_tr_b16 v[252:253], v151 offset:6656
	s_waitcnt lgkmcnt(12)
	v_mfma_f32_32x32x16_bf16 v[80:95], v[222:225], v[112:115], v[80:95]
	v_exp_f32_e32 v164, v164
	v_exp_f32_e32 v165, v165
	v_add_f32_e32 v234, v234, v162
	ds_read_b64_tr_b16 v[152:153], v151 offset:5120
	ds_read_b64_tr_b16 v[154:155], v151 offset:7168
	s_waitcnt lgkmcnt(12)
	v_mfma_f32_32x32x16_bf16 v[48:63], v[178:181], v[226:229], v[48:63]
	v_exp_f32_e32 v166, v166
	v_exp_f32_e32 v167, v167
	v_add_f32_e32 v235, v235, v163
	v_add_f32_e32 v234, v234, v164
	ds_read_b64_tr_b16 v[226:227], v151 offset:5632
	ds_read_b64_tr_b16 v[228:229], v151 offset:7680
	s_waitcnt lgkmcnt(12)
	v_mfma_f32_32x32x16_bf16 v[32:47], v[178:181], v[230:233], v[32:47]
	v_exp_f32_e32 v168, v168
	v_exp_f32_e32 v169, v169
	v_add_f32_e32 v235, v235, v165
	v_add_f32_e32 v234, v234, v166
	ds_read_b64_tr_b16 v[230:231], v151 offset:8192
	ds_read_b64_tr_b16 v[232:233], v151 offset:10240
	s_waitcnt lgkmcnt(12)
	v_mfma_f32_32x32x16_bf16 v[16:31], v[178:181], v[238:241], v[16:31]
	v_add_f32_e32 v235, v235, v167
	v_add_f32_e32 v234, v234, v168
	v_add_f32_e32 v235, v235, v169
	v_cvt_pk_bf16_f32 v186, v162, v163
	v_cvt_pk_bf16_f32 v188, v166, v167
	ds_read_b64_tr_b16 v[238:239], v151 offset:8704
	ds_read_b64_tr_b16 v[240:241], v151 offset:10752
	s_waitcnt lgkmcnt(12)
	v_mfma_f32_32x32x16_bf16 v[0:15], v[178:181], v[242:245], v[0:15]
	v_cvt_pk_bf16_f32 v187, v164, v165
	v_cvt_pk_bf16_f32 v189, v168, v169
	ds_read_b64_tr_b16 v[242:243], v151 offset:9216
	ds_read_b64_tr_b16 v[244:245], v151 offset:11264
	s_waitcnt lgkmcnt(12)
	v_mfma_f32_32x32x16_bf16 v[48:63], v[182:185], v[246:249], v[48:63]
	v_exp_f32_e32 v170, v170
	v_exp_f32_e32 v171, v171
	ds_read_b64_tr_b16 v[246:247], v151 offset:9728
	ds_read_b64_tr_b16 v[248:249], v151 offset:11776
	s_waitcnt lgkmcnt(12)
	v_mfma_f32_32x32x16_bf16 v[32:47], v[182:185], v[250:253], v[32:47]
	v_exp_f32_e32 v172, v172
	v_exp_f32_e32 v173, v173
	v_add_f32_e32 v234, v234, v170
	ds_read_b64_tr_b16 v[250:251], v151 offset:12288
	ds_read_b64_tr_b16 v[252:253], v151 offset:14336
	s_waitcnt lgkmcnt(12)
	v_mfma_f32_32x32x16_bf16 v[16:31], v[182:185], v[152:155], v[16:31]
	v_exp_f32_e32 v174, v174
	v_exp_f32_e32 v175, v175
	v_add_f32_e32 v235, v235, v171
	v_add_f32_e32 v234, v234, v172
	ds_read_b64_tr_b16 v[152:153], v151 offset:12800
	ds_read_b64_tr_b16 v[154:155], v151 offset:14848
	s_waitcnt lgkmcnt(12)
	v_mfma_f32_32x32x16_bf16 v[0:15], v[182:185], v[226:229], v[0:15]
	v_exp_f32_e32 v176, v176
	v_exp_f32_e32 v177, v177
	v_add_f32_e32 v235, v235, v173
	v_add_f32_e32 v234, v234, v174
	ds_read_b64_tr_b16 v[226:227], v151 offset:13312
	ds_read_b64_tr_b16 v[228:229], v151 offset:15360
	s_waitcnt lgkmcnt(12)
	v_mfma_f32_32x32x16_bf16 v[48:63], v[186:189], v[230:233], v[48:63]
	v_add_f32_e32 v235, v235, v175
	v_add_f32_e32 v234, v234, v176
	v_add_f32_e32 v235, v235, v177
	v_cvt_pk_bf16_f32 v190, v170, v171
	v_cvt_pk_bf16_f32 v192, v174, v175
	ds_read_b64_tr_b16 v[230:231], v151 offset:13824
	ds_read_b64_tr_b16 v[232:233], v151 offset:15872
	s_waitcnt lgkmcnt(12)
	v_mfma_f32_32x32x16_bf16 v[32:47], v[186:189], v[238:241], v[32:47]
	s_add_i32 s62, s62, 0x4000
	s_cmp_ge_u32 s62, 0x14000
	s_cselect_b32 s69, 0x14000, 0
	s_sub_i32 s62, s62, s69
	v_add_u32_e32 v151, s62, v140
	v_cvt_pk_bf16_f32 v191, v172, v173
	v_cvt_pk_bf16_f32 v193, v176, v177
	s_waitcnt lgkmcnt(10)
	v_mfma_f32_32x32x16_bf16 v[16:31], v[186:189], v[242:245], v[16:31]
	v_exp_f32_e32 v64, v64
	v_exp_f32_e32 v65, v65
	ds_read_b128 v[194:197], v149 offset:49152
	s_waitcnt lgkmcnt(9)
	v_mfma_f32_32x32x16_bf16 v[0:15], v[186:189], v[246:249], v[0:15]
	v_exp_f32_e32 v66, v66
	v_exp_f32_e32 v67, v67
	v_add_f32_e32 v234, v234, v64
	ds_read_b128 v[198:201], v148 offset:49152
	s_waitcnt lgkmcnt(8)
	v_mfma_f32_32x32x16_bf16 v[48:63], v[190:193], v[250:253], v[48:63]
	v_exp_f32_e32 v68, v68
	v_exp_f32_e32 v69, v69
	v_add_f32_e32 v235, v235, v65
	v_add_f32_e32 v234, v234, v66
	ds_read_b128 v[202:205], v143 offset:49152
	s_waitcnt lgkmcnt(7)
	v_mfma_f32_32x32x16_bf16 v[32:47], v[190:193], v[152:155], v[32:47]
	v_exp_f32_e32 v70, v70
	v_exp_f32_e32 v71, v71
	v_add_f32_e32 v235, v235, v67
	v_add_f32_e32 v234, v234, v68
	ds_read_b128 v[206:209], v141 offset:49152
	s_waitcnt lgkmcnt(6)
	v_mfma_f32_32x32x16_bf16 v[16:31], v[190:193], v[226:229], v[16:31]
	v_add_f32_e32 v235, v235, v69
	v_add_f32_e32 v234, v234, v70
	v_add_f32_e32 v235, v235, v71
	v_cvt_pk_bf16_f32 v178, v64, v65
	v_cvt_pk_bf16_f32 v180, v68, v69
	ds_read_b128 v[210:213], v149 offset:57344
	s_waitcnt lgkmcnt(5)
	v_mfma_f32_32x32x16_bf16 v[0:15], v[190:193], v[230:233], v[0:15]
	v_cvt_pk_bf16_f32 v179, v66, v67
	v_cvt_pk_bf16_f32 v181, v70, v71
	ds_read_b128 v[214:217], v148 offset:57344
	s_waitcnt lgkmcnt(5)
	v_mfma_f32_32x32x16_bf16 v[96:111], v[194:197], v[124:127], 0
	v_exp_f32_e32 v72, v72
	v_exp_f32_e32 v73, v73
	ds_read_b128 v[218:221], v143 offset:57344
	s_waitcnt lgkmcnt(5)
	v_mfma_f32_32x32x16_bf16 v[96:111], v[198:201], v[120:123], v[96:111]
	v_exp_f32_e32 v74, v74
	v_exp_f32_e32 v75, v75
	v_add_f32_e32 v234, v234, v72
	ds_read_b128 v[222:225], v141 offset:57344
	ds_read_b64_tr_b16 v[226:227], v151 offset:0
	ds_read_b64_tr_b16 v[228:229], v151 offset:2048
	s_waitcnt lgkmcnt(7)
	v_mfma_f32_32x32x16_bf16 v[96:111], v[202:205], v[116:119], v[96:111]
	v_exp_f32_e32 v76, v76
	v_exp_f32_e32 v77, v77
	v_add_f32_e32 v235, v235, v73
	v_add_f32_e32 v234, v234, v74
	ds_read_b64_tr_b16 v[230:231], v151 offset:512
	ds_read_b64_tr_b16 v[232:233], v151 offset:2560
	s_waitcnt lgkmcnt(8)
	v_mfma_f32_32x32x16_bf16 v[96:111], v[206:209], v[112:115], v[96:111]
	v_exp_f32_e32 v78, v78
	v_exp_f32_e32 v79, v79
	v_add_f32_e32 v235, v235, v75
	v_add_f32_e32 v234, v234, v76
	ds_read_b64_tr_b16 v[238:239], v151 offset:1024
	ds_read_b64_tr_b16 v[240:241], v151 offset:3072
	s_waitcnt lgkmcnt(9)
	v_mfma_f32_32x32x16_bf16 v[162:177], v[210:213], v[124:127], 0
	v_add_f32_e32 v235, v235, v77
	v_add_f32_e32 v234, v234, v78
	v_add_f32_e32 v235, v235, v79
	v_cvt_pk_bf16_f32 v182, v72, v73
	v_cvt_pk_bf16_f32 v184, v76, v77
	ds_read_b64_tr_b16 v[242:243], v151 offset:1536
	ds_read_b64_tr_b16 v[244:245], v151 offset:3584
	s_waitcnt lgkmcnt(10)
	v_mfma_f32_32x32x16_bf16 v[162:177], v[214:217], v[120:123], v[162:177]
	v_cvt_pk_bf16_f32 v183, v74, v75
	v_cvt_pk_bf16_f32 v185, v78, v79
	ds_read_b64_tr_b16 v[246:247], v151 offset:4096
	ds_read_b64_tr_b16 v[248:249], v151 offset:6144
	s_waitcnt lgkmcnt(11)
	v_mfma_f32_32x32x16_bf16 v[162:177], v[218:221], v[116:119], v[162:177]
	v_exp_f32_e32 v80, v80
	v_exp_f32_e32 v81, v81
	ds_read_b64_tr_b16 v[250:251], v151 offset:4608
	ds_read_b64_tr_b16 v[252:253], v151 offset:6656
	s_waitcnt lgkmcnt(12)
	v_mfma_f32_32x32x16_bf16 v[162:177], v[222:225], v[112:115], v[162:177]
	v_exp_f32_e32 v82, v82
	v_exp_f32_e32 v83, v83
	v_add_f32_e32 v234, v234, v80
	ds_read_b64_tr_b16 v[152:153], v151 offset:5120
	ds_read_b64_tr_b16 v[154:155], v151 offset:7168
	s_waitcnt lgkmcnt(12)
	v_mfma_f32_32x32x16_bf16 v[48:63], v[178:181], v[226:229], v[48:63]
	v_exp_f32_e32 v84, v84
	v_exp_f32_e32 v85, v85
	v_add_f32_e32 v235, v235, v81
	v_add_f32_e32 v234, v234, v82
	ds_read_b64_tr_b16 v[226:227], v151 offset:5632
	ds_read_b64_tr_b16 v[228:229], v151 offset:7680
	s_waitcnt lgkmcnt(12)
	v_mfma_f32_32x32x16_bf16 v[32:47], v[178:181], v[230:233], v[32:47]
	v_exp_f32_e32 v86, v86
	v_exp_f32_e32 v87, v87
	v_add_f32_e32 v235, v235, v83
	v_add_f32_e32 v234, v234, v84
	ds_read_b64_tr_b16 v[230:231], v151 offset:8192
	ds_read_b64_tr_b16 v[232:233], v151 offset:10240
	s_waitcnt lgkmcnt(12)
	v_mfma_f32_32x32x16_bf16 v[16:31], v[178:181], v[238:241], v[16:31]
	v_add_f32_e32 v235, v235, v85
	v_add_f32_e32 v234, v234, v86
	v_add_f32_e32 v235, v235, v87
	v_cvt_pk_bf16_f32 v186, v80, v81
	v_cvt_pk_bf16_f32 v188, v84, v85
	ds_read_b64_tr_b16 v[238:239], v151 offset:8704
	ds_read_b64_tr_b16 v[240:241], v151 offset:10752
	s_waitcnt lgkmcnt(12)
	v_mfma_f32_32x32x16_bf16 v[0:15], v[178:181], v[242:245], v[0:15]
	v_cvt_pk_bf16_f32 v187, v82, v83
	v_cvt_pk_bf16_f32 v189, v86, v87
	ds_read_b64_tr_b16 v[242:243], v151 offset:9216
	ds_read_b64_tr_b16 v[244:245], v151 offset:11264
	s_waitcnt lgkmcnt(12)
	v_mfma_f32_32x32x16_bf16 v[48:63], v[182:185], v[246:249], v[48:63]
	v_exp_f32_e32 v88, v88
	v_exp_f32_e32 v89, v89
	ds_read_b64_tr_b16 v[246:247], v151 offset:9728
	ds_read_b64_tr_b16 v[248:249], v151 offset:11776
	s_waitcnt lgkmcnt(12)
	v_mfma_f32_32x32x16_bf16 v[32:47], v[182:185], v[250:253], v[32:47]
	v_exp_f32_e32 v90, v90
	v_exp_f32_e32 v91, v91
	v_add_f32_e32 v234, v234, v88
	ds_read_b64_tr_b16 v[250:251], v151 offset:12288
	ds_read_b64_tr_b16 v[252:253], v151 offset:14336
	s_waitcnt lgkmcnt(12)
	v_mfma_f32_32x32x16_bf16 v[16:31], v[182:185], v[152:155], v[16:31]
	v_exp_f32_e32 v92, v92
	v_exp_f32_e32 v93, v93
	v_add_f32_e32 v235, v235, v89
	v_add_f32_e32 v234, v234, v90
	ds_read_b64_tr_b16 v[152:153], v151 offset:12800
	ds_read_b64_tr_b16 v[154:155], v151 offset:14848
	s_waitcnt lgkmcnt(12)
	v_mfma_f32_32x32x16_bf16 v[0:15], v[182:185], v[226:229], v[0:15]
	v_exp_f32_e32 v94, v94
	v_exp_f32_e32 v95, v95
	v_add_f32_e32 v235, v235, v91
	v_add_f32_e32 v234, v234, v92
	ds_read_b64_tr_b16 v[226:227], v151 offset:13312
	ds_read_b64_tr_b16 v[228:229], v151 offset:15360
	s_waitcnt lgkmcnt(12)
	v_mfma_f32_32x32x16_bf16 v[48:63], v[186:189], v[230:233], v[48:63]
	v_add_f32_e32 v235, v235, v93
	v_add_f32_e32 v234, v234, v94
	v_add_f32_e32 v235, v235, v95
	v_cvt_pk_bf16_f32 v190, v88, v89
	v_cvt_pk_bf16_f32 v192, v92, v93
	ds_read_b64_tr_b16 v[230:231], v151 offset:13824
	ds_read_b64_tr_b16 v[232:233], v151 offset:15872
	s_waitcnt lgkmcnt(12)
	v_mfma_f32_32x32x16_bf16 v[32:47], v[186:189], v[238:241], v[32:47]
	s_waitcnt vmcnt(0)
	s_barrier
	s_add_i32 s63, s62, 0xc000
	s_cmp_ge_u32 s63, 0x14000
	s_cselect_b32 s69, 0x14000, 0
	s_sub_i32 s63, s63, s69
	s_add_i32 s68, s62, 0x10000
	s_cmp_ge_u32 s68, 0x14000
	s_cselect_b32 s69, 0x14000, 0
	s_sub_i32 s68, s68, s69
	s_add_i32 s62, s62, 0x4000
	s_cmp_ge_u32 s62, 0x14000
	s_cselect_b32 s69, 0x14000, 0
	s_sub_i32 s62, s62, s69
	v_add_u32_e32 v151, s62, v140
	v_cvt_pk_bf16_f32 v191, v90, v91
	v_cvt_pk_bf16_f32 v193, v94, v95
	s_add_i32 m0, s41, s63
	s_add_u32 s42, s46, 0x5d81000
	s_addc_u32 s43, s47, 0
	global_load_lds_dwordx4 v150, s[42:43]
	s_waitcnt lgkmcnt(10)
	v_mfma_f32_32x32x16_bf16 v[16:31], v[186:189], v[242:245], v[16:31]
	v_exp_f32_e32 v96, v96
	v_exp_f32_e32 v97, v97
	ds_read_b128 v[194:197], v149 offset:0
	s_add_i32 m0, s71, s63
	s_add_u32 s42, s46, 0x5dc1000
	s_addc_u32 s43, s47, 0
	global_load_lds_dwordx4 v150, s[42:43]
	s_waitcnt lgkmcnt(9)
	v_mfma_f32_32x32x16_bf16 v[0:15], v[186:189], v[246:249], v[0:15]
	v_exp_f32_e32 v98, v98
	v_exp_f32_e32 v99, v99
	v_add_f32_e32 v234, v234, v96
	ds_read_b128 v[198:201], v148 offset:0
	s_add_i32 m0, s40, 0x8000
	s_add_u32 s42, s72, 0x5e00800
	s_addc_u32 s43, s73, 0
	global_load_lds_dwordx4 v142, s[42:43]
	s_waitcnt lgkmcnt(8)
	v_mfma_f32_32x32x16_bf16 v[48:63], v[190:193], v[250:253], v[48:63]
	v_exp_f32_e32 v100, v100
	v_exp_f32_e32 v101, v101
	v_add_f32_e32 v235, v235, v97
	v_add_f32_e32 v234, v234, v98
	ds_read_b128 v[202:205], v143 offset:0
	s_add_i32 m0, s40, 0xa000
	s_add_u32 s42, s72, 0x5e40800
	s_addc_u32 s43, s73, 0
	global_load_lds_dwordx4 v142, s[42:43]
	s_waitcnt lgkmcnt(7)
	v_mfma_f32_32x32x16_bf16 v[32:47], v[190:193], v[152:155], v[32:47]
	v_exp_f32_e32 v102, v102
	v_exp_f32_e32 v103, v103
	v_add_f32_e32 v235, v235, v99
	v_add_f32_e32 v234, v234, v100
	ds_read_b128 v[206:209], v141 offset:0
	s_add_i32 m0, s41, s68
	s_add_u32 s42, s46, 0x5e01000
	s_addc_u32 s43, s47, 0
	global_load_lds_dwordx4 v150, s[42:43]
	s_waitcnt lgkmcnt(6)
	v_mfma_f32_32x32x16_bf16 v[16:31], v[190:193], v[226:229], v[16:31]
	v_add_f32_e32 v235, v235, v101
	v_add_f32_e32 v234, v234, v102
	v_add_f32_e32 v235, v235, v103
	v_cvt_pk_bf16_f32 v178, v96, v97
	v_cvt_pk_bf16_f32 v180, v100, v101
	ds_read_b128 v[210:213], v149 offset:8192
	s_add_i32 m0, s71, s68
	s_add_u32 s42, s46, 0x5e41000
	s_addc_u32 s43, s47, 0
	global_load_lds_dwordx4 v150, s[42:43]
	s_waitcnt lgkmcnt(5)
	v_mfma_f32_32x32x16_bf16 v[0:15], v[190:193], v[230:233], v[0:15]
	v_cvt_pk_bf16_f32 v179, v98, v99
	v_cvt_pk_bf16_f32 v181, v102, v103
	ds_read_b128 v[214:217], v148 offset:8192
	s_add_i32 m0, s40, 0xc000
	s_add_u32 s42, s72, 0x5e80800
	s_addc_u32 s43, s73, 0
	global_load_lds_dwordx4 v142, s[42:43]
	s_add_i32 m0, s40, 0xe000
	s_add_u32 s42, s72, 0x5ec0800
	s_addc_u32 s43, s73, 0
	global_load_lds_dwordx4 v142, s[42:43]
	s_add_u32 s72, s72, 0x100000
	s_addc_u32 s73, s73, 0
	s_add_u32 s46, s46, 0x100000
	s_addc_u32 s47, s47, 0
	s_waitcnt lgkmcnt(5)
	v_mfma_f32_32x32x16_bf16 v[64:79], v[194:197], v[124:127], 0
	v_exp_f32_e32 v104, v104
	v_exp_f32_e32 v105, v105
	ds_read_b128 v[218:221], v143 offset:8192
	s_waitcnt lgkmcnt(5)
	v_mfma_f32_32x32x16_bf16 v[64:79], v[198:201], v[120:123], v[64:79]
	v_exp_f32_e32 v106, v106
	v_exp_f32_e32 v107, v107
	v_add_f32_e32 v234, v234, v104
	ds_read_b128 v[222:225], v141 offset:8192
	ds_read_b64_tr_b16 v[226:227], v151 offset:0
	ds_read_b64_tr_b16 v[228:229], v151 offset:2048
	s_waitcnt lgkmcnt(7)
	v_mfma_f32_32x32x16_bf16 v[64:79], v[202:205], v[116:119], v[64:79]
	v_exp_f32_e32 v108, v108
	v_exp_f32_e32 v109, v109
	v_add_f32_e32 v235, v235, v105
	v_add_f32_e32 v234, v234, v106
	ds_read_b64_tr_b16 v[230:231], v151 offset:512
	ds_read_b64_tr_b16 v[232:233], v151 offset:2560
	s_waitcnt lgkmcnt(8)
	v_mfma_f32_32x32x16_bf16 v[64:79], v[206:209], v[112:115], v[64:79]
	v_exp_f32_e32 v110, v110
	v_exp_f32_e32 v111, v111
	v_add_f32_e32 v235, v235, v107
	v_add_f32_e32 v234, v234, v108
	ds_read_b64_tr_b16 v[238:239], v151 offset:1024
	ds_read_b64_tr_b16 v[240:241], v151 offset:3072
	s_waitcnt lgkmcnt(9)
	v_mfma_f32_32x32x16_bf16 v[80:95], v[210:213], v[124:127], 0
	v_add_f32_e32 v235, v235, v109
	v_add_f32_e32 v234, v234, v110
	v_add_f32_e32 v235, v235, v111
	v_cvt_pk_bf16_f32 v182, v104, v105
	v_cvt_pk_bf16_f32 v184, v108, v109
	ds_read_b64_tr_b16 v[242:243], v151 offset:1536
	ds_read_b64_tr_b16 v[244:245], v151 offset:3584
	s_waitcnt lgkmcnt(10)
	v_mfma_f32_32x32x16_bf16 v[80:95], v[214:217], v[120:123], v[80:95]
	v_cvt_pk_bf16_f32 v183, v106, v107
	v_cvt_pk_bf16_f32 v185, v110, v111
	ds_read_b64_tr_b16 v[246:247], v151 offset:4096
	ds_read_b64_tr_b16 v[248:249], v151 offset:6144
	s_waitcnt lgkmcnt(11)
	v_mfma_f32_32x32x16_bf16 v[80:95], v[218:221], v[116:119], v[80:95]
	v_exp_f32_e32 v162, v162
	v_exp_f32_e32 v163, v163
	ds_read_b64_tr_b16 v[250:251], v151 offset:4608
	ds_read_b64_tr_b16 v[252:253], v151 offset:6656
	s_waitcnt lgkmcnt(12)
	v_mfma_f32_32x32x16_bf16 v[80:95], v[222:225], v[112:115], v[80:95]
	v_exp_f32_e32 v164, v164
	v_exp_f32_e32 v165, v165
	v_add_f32_e32 v234, v234, v162
	ds_read_b64_tr_b16 v[152:153], v151 offset:5120
	ds_read_b64_tr_b16 v[154:155], v151 offset:7168
	s_waitcnt lgkmcnt(12)
	v_mfma_f32_32x32x16_bf16 v[48:63], v[178:181], v[226:229], v[48:63]
	v_exp_f32_e32 v166, v166
	v_exp_f32_e32 v167, v167
	v_add_f32_e32 v235, v235, v163
	v_add_f32_e32 v234, v234, v164
	ds_read_b64_tr_b16 v[226:227], v151 offset:5632
	ds_read_b64_tr_b16 v[228:229], v151 offset:7680
	s_waitcnt lgkmcnt(12)
	v_mfma_f32_32x32x16_bf16 v[32:47], v[178:181], v[230:233], v[32:47]
	v_exp_f32_e32 v168, v168
	v_exp_f32_e32 v169, v169
	v_add_f32_e32 v235, v235, v165
	v_add_f32_e32 v234, v234, v166
	ds_read_b64_tr_b16 v[230:231], v151 offset:8192
	ds_read_b64_tr_b16 v[232:233], v151 offset:10240
	s_waitcnt lgkmcnt(12)
	v_mfma_f32_32x32x16_bf16 v[16:31], v[178:181], v[238:241], v[16:31]
	v_add_f32_e32 v235, v235, v167
	v_add_f32_e32 v234, v234, v168
	v_add_f32_e32 v235, v235, v169
	v_cvt_pk_bf16_f32 v186, v162, v163
	v_cvt_pk_bf16_f32 v188, v166, v167
	ds_read_b64_tr_b16 v[238:239], v151 offset:8704
	ds_read_b64_tr_b16 v[240:241], v151 offset:10752
	s_waitcnt lgkmcnt(12)
	v_mfma_f32_32x32x16_bf16 v[0:15], v[178:181], v[242:245], v[0:15]
	v_cvt_pk_bf16_f32 v187, v164, v165
	v_cvt_pk_bf16_f32 v189, v168, v169
	ds_read_b64_tr_b16 v[242:243], v151 offset:9216
	ds_read_b64_tr_b16 v[244:245], v151 offset:11264
	s_waitcnt lgkmcnt(12)
	v_mfma_f32_32x32x16_bf16 v[48:63], v[182:185], v[246:249], v[48:63]
	v_exp_f32_e32 v170, v170
	v_exp_f32_e32 v171, v171
	ds_read_b64_tr_b16 v[246:247], v151 offset:9728
	ds_read_b64_tr_b16 v[248:249], v151 offset:11776
	s_waitcnt lgkmcnt(12)
	v_mfma_f32_32x32x16_bf16 v[32:47], v[182:185], v[250:253], v[32:47]
	v_exp_f32_e32 v172, v172
	v_exp_f32_e32 v173, v173
	v_add_f32_e32 v234, v234, v170
	ds_read_b64_tr_b16 v[250:251], v151 offset:12288
	ds_read_b64_tr_b16 v[252:253], v151 offset:14336
	s_waitcnt lgkmcnt(12)
	v_mfma_f32_32x32x16_bf16 v[16:31], v[182:185], v[152:155], v[16:31]
	v_exp_f32_e32 v174, v174
	v_exp_f32_e32 v175, v175
	v_add_f32_e32 v235, v235, v171
	v_add_f32_e32 v234, v234, v172
	ds_read_b64_tr_b16 v[152:153], v151 offset:12800
	ds_read_b64_tr_b16 v[154:155], v151 offset:14848
	s_waitcnt lgkmcnt(12)
	v_mfma_f32_32x32x16_bf16 v[0:15], v[182:185], v[226:229], v[0:15]
	v_exp_f32_e32 v176, v176
	v_exp_f32_e32 v177, v177
	v_add_f32_e32 v235, v235, v173
	v_add_f32_e32 v234, v234, v174
	ds_read_b64_tr_b16 v[226:227], v151 offset:13312
	ds_read_b64_tr_b16 v[228:229], v151 offset:15360
	s_waitcnt lgkmcnt(12)
	v_mfma_f32_32x32x16_bf16 v[48:63], v[186:189], v[230:233], v[48:63]
	v_add_f32_e32 v235, v235, v175
	v_add_f32_e32 v234, v234, v176
	v_add_f32_e32 v235, v235, v177
	v_cvt_pk_bf16_f32 v190, v170, v171
	v_cvt_pk_bf16_f32 v192, v174, v175
	ds_read_b64_tr_b16 v[230:231], v151 offset:13824
	ds_read_b64_tr_b16 v[232:233], v151 offset:15872
	s_waitcnt lgkmcnt(12)
	v_mfma_f32_32x32x16_bf16 v[32:47], v[186:189], v[238:241], v[32:47]
	s_add_i32 s62, s62, 0x4000
	s_cmp_ge_u32 s62, 0x14000
	s_cselect_b32 s69, 0x14000, 0
	s_sub_i32 s62, s62, s69
	v_add_u32_e32 v151, s62, v140
	v_cvt_pk_bf16_f32 v191, v172, v173
	v_cvt_pk_bf16_f32 v193, v176, v177
	s_waitcnt lgkmcnt(10)
	v_mfma_f32_32x32x16_bf16 v[16:31], v[186:189], v[242:245], v[16:31]
	v_exp_f32_e32 v64, v64
	v_exp_f32_e32 v65, v65
	ds_read_b128 v[194:197], v149 offset:16384
	s_waitcnt lgkmcnt(9)
	v_mfma_f32_32x32x16_bf16 v[0:15], v[186:189], v[246:249], v[0:15]
	v_exp_f32_e32 v66, v66
	v_exp_f32_e32 v67, v67
	v_add_f32_e32 v234, v234, v64
	ds_read_b128 v[198:201], v148 offset:16384
	s_waitcnt lgkmcnt(8)
	v_mfma_f32_32x32x16_bf16 v[48:63], v[190:193], v[250:253], v[48:63]
	v_exp_f32_e32 v68, v68
	v_exp_f32_e32 v69, v69
	v_add_f32_e32 v235, v235, v65
	v_add_f32_e32 v234, v234, v66
	ds_read_b128 v[202:205], v143 offset:16384
	s_waitcnt lgkmcnt(7)
	v_mfma_f32_32x32x16_bf16 v[32:47], v[190:193], v[152:155], v[32:47]
	v_exp_f32_e32 v70, v70
	v_exp_f32_e32 v71, v71
	v_add_f32_e32 v235, v235, v67
	v_add_f32_e32 v234, v234, v68
	ds_read_b128 v[206:209], v141 offset:16384
	s_waitcnt lgkmcnt(6)
	v_mfma_f32_32x32x16_bf16 v[16:31], v[190:193], v[226:229], v[16:31]
	v_add_f32_e32 v235, v235, v69
	v_add_f32_e32 v234, v234, v70
	v_add_f32_e32 v235, v235, v71
	v_cvt_pk_bf16_f32 v178, v64, v65
	v_cvt_pk_bf16_f32 v180, v68, v69
	ds_read_b128 v[210:213], v149 offset:24576
	s_waitcnt lgkmcnt(5)
	v_mfma_f32_32x32x16_bf16 v[0:15], v[190:193], v[230:233], v[0:15]
	v_cvt_pk_bf16_f32 v179, v66, v67
	v_cvt_pk_bf16_f32 v181, v70, v71
	ds_read_b128 v[214:217], v148 offset:24576
	s_sub_i32 s70, s70, 1
	s_cmp_lg_u32 s70, 0
	s_cbranch_scc1 .Lda_loop
	s_waitcnt lgkmcnt(5)
	v_mfma_f32_32x32x16_bf16 v[96:111], v[194:197], v[124:127], 0
	v_exp_f32_e32 v72, v72
	v_exp_f32_e32 v73, v73
	ds_read_b128 v[218:221], v143 offset:24576
	s_waitcnt lgkmcnt(5)
	v_mfma_f32_32x32x16_bf16 v[96:111], v[198:201], v[120:123], v[96:111]
	v_exp_f32_e32 v74, v74
	v_exp_f32_e32 v75, v75
	v_add_f32_e32 v234, v234, v72
	ds_read_b128 v[222:225], v141 offset:24576
	ds_read_b64_tr_b16 v[226:227], v151 offset:0
	ds_read_b64_tr_b16 v[228:229], v151 offset:2048
	s_waitcnt lgkmcnt(7)
	v_mfma_f32_32x32x16_bf16 v[96:111], v[202:205], v[116:119], v[96:111]
	v_exp_f32_e32 v76, v76
	v_exp_f32_e32 v77, v77
	v_add_f32_e32 v235, v235, v73
	v_add_f32_e32 v234, v234, v74
	ds_read_b64_tr_b16 v[230:231], v151 offset:512
	ds_read_b64_tr_b16 v[232:233], v151 offset:2560
	s_waitcnt lgkmcnt(8)
	v_mfma_f32_32x32x16_bf16 v[96:111], v[206:209], v[112:115], v[96:111]
	v_exp_f32_e32 v78, v78
	v_exp_f32_e32 v79, v79
	v_add_f32_e32 v235, v235, v75
	v_add_f32_e32 v234, v234, v76
	ds_read_b64_tr_b16 v[238:239], v151 offset:1024
	ds_read_b64_tr_b16 v[240:241], v151 offset:3072
	s_waitcnt lgkmcnt(9)
	v_mfma_f32_32x32x16_bf16 v[162:177], v[210:213], v[124:127], 0
	v_add_f32_e32 v235, v235, v77
	v_add_f32_e32 v234, v234, v78
	v_add_f32_e32 v235, v235, v79
	v_cvt_pk_bf16_f32 v182, v72, v73
	v_cvt_pk_bf16_f32 v184, v76, v77
	ds_read_b64_tr_b16 v[242:243], v151 offset:1536
	ds_read_b64_tr_b16 v[244:245], v151 offset:3584
	s_waitcnt lgkmcnt(10)
	v_mfma_f32_32x32x16_bf16 v[162:177], v[214:217], v[120:123], v[162:177]
	v_cvt_pk_bf16_f32 v183, v74, v75
	v_cvt_pk_bf16_f32 v185, v78, v79
	ds_read_b64_tr_b16 v[246:247], v151 offset:4096
	ds_read_b64_tr_b16 v[248:249], v151 offset:6144
	s_waitcnt lgkmcnt(11)
	v_mfma_f32_32x32x16_bf16 v[162:177], v[218:221], v[116:119], v[162:177]
	v_exp_f32_e32 v80, v80
	v_exp_f32_e32 v81, v81
	ds_read_b64_tr_b16 v[250:251], v151 offset:4608
	ds_read_b64_tr_b16 v[252:253], v151 offset:6656
	s_waitcnt lgkmcnt(12)
	v_mfma_f32_32x32x16_bf16 v[162:177], v[222:225], v[112:115], v[162:177]
	v_exp_f32_e32 v82, v82
	v_exp_f32_e32 v83, v83
	v_add_f32_e32 v234, v234, v80
	ds_read_b64_tr_b16 v[152:153], v151 offset:5120
	ds_read_b64_tr_b16 v[154:155], v151 offset:7168
	s_waitcnt lgkmcnt(12)
	v_mfma_f32_32x32x16_bf16 v[48:63], v[178:181], v[226:229], v[48:63]
	v_exp_f32_e32 v84, v84
	v_exp_f32_e32 v85, v85
	v_add_f32_e32 v235, v235, v81
	v_add_f32_e32 v234, v234, v82
	ds_read_b64_tr_b16 v[226:227], v151 offset:5632
	ds_read_b64_tr_b16 v[228:229], v151 offset:7680
	s_waitcnt lgkmcnt(12)
	v_mfma_f32_32x32x16_bf16 v[32:47], v[178:181], v[230:233], v[32:47]
	v_exp_f32_e32 v86, v86
	v_exp_f32_e32 v87, v87
	v_add_f32_e32 v235, v235, v83
	v_add_f32_e32 v234, v234, v84
	ds_read_b64_tr_b16 v[230:231], v151 offset:8192
	ds_read_b64_tr_b16 v[232:233], v151 offset:10240
	s_waitcnt lgkmcnt(12)
	v_mfma_f32_32x32x16_bf16 v[16:31], v[178:181], v[238:241], v[16:31]
	v_add_f32_e32 v235, v235, v85
	v_add_f32_e32 v234, v234, v86
	v_add_f32_e32 v235, v235, v87
	v_cvt_pk_bf16_f32 v186, v80, v81
	v_cvt_pk_bf16_f32 v188, v84, v85
	ds_read_b64_tr_b16 v[238:239], v151 offset:8704
	ds_read_b64_tr_b16 v[240:241], v151 offset:10752
	s_waitcnt lgkmcnt(12)
	v_mfma_f32_32x32x16_bf16 v[0:15], v[178:181], v[242:245], v[0:15]
	v_cvt_pk_bf16_f32 v187, v82, v83
	v_cvt_pk_bf16_f32 v189, v86, v87
	ds_read_b64_tr_b16 v[242:243], v151 offset:9216
	ds_read_b64_tr_b16 v[244:245], v151 offset:11264
	s_waitcnt lgkmcnt(12)
	v_mfma_f32_32x32x16_bf16 v[48:63], v[182:185], v[246:249], v[48:63]
	v_exp_f32_e32 v88, v88
	v_exp_f32_e32 v89, v89
	ds_read_b64_tr_b16 v[246:247], v151 offset:9728
	ds_read_b64_tr_b16 v[248:249], v151 offset:11776
	s_waitcnt lgkmcnt(12)
	v_mfma_f32_32x32x16_bf16 v[32:47], v[182:185], v[250:253], v[32:47]
	v_exp_f32_e32 v90, v90
	v_exp_f32_e32 v91, v91
	v_add_f32_e32 v234, v234, v88
	ds_read_b64_tr_b16 v[250:251], v151 offset:12288
	ds_read_b64_tr_b16 v[252:253], v151 offset:14336
	s_waitcnt lgkmcnt(12)
	v_mfma_f32_32x32x16_bf16 v[16:31], v[182:185], v[152:155], v[16:31]
	v_exp_f32_e32 v92, v92
	v_exp_f32_e32 v93, v93
	v_add_f32_e32 v235, v235, v89
	v_add_f32_e32 v234, v234, v90
	ds_read_b64_tr_b16 v[152:153], v151 offset:12800
	ds_read_b64_tr_b16 v[154:155], v151 offset:14848
	s_waitcnt lgkmcnt(12)
	v_mfma_f32_32x32x16_bf16 v[0:15], v[182:185], v[226:229], v[0:15]
	v_exp_f32_e32 v94, v94
	v_exp_f32_e32 v95, v95
	v_add_f32_e32 v235, v235, v91
	v_add_f32_e32 v234, v234, v92
	ds_read_b64_tr_b16 v[226:227], v151 offset:13312
	ds_read_b64_tr_b16 v[228:229], v151 offset:15360
	s_waitcnt lgkmcnt(12)
	v_mfma_f32_32x32x16_bf16 v[48:63], v[186:189], v[230:233], v[48:63]
	v_add_f32_e32 v235, v235, v93
	v_add_f32_e32 v234, v234, v94
	v_add_f32_e32 v235, v235, v95
	v_cvt_pk_bf16_f32 v190, v88, v89
	v_cvt_pk_bf16_f32 v192, v92, v93
	ds_read_b64_tr_b16 v[230:231], v151 offset:13824
	ds_read_b64_tr_b16 v[232:233], v151 offset:15872
	s_waitcnt lgkmcnt(12)
	v_mfma_f32_32x32x16_bf16 v[32:47], v[186:189], v[238:241], v[32:47]
	s_waitcnt vmcnt(0)
	s_barrier
	s_add_i32 s63, s62, 0xc000
	s_cmp_ge_u32 s63, 0x14000
	s_cselect_b32 s69, 0x14000, 0
	s_sub_i32 s63, s63, s69
	s_add_i32 s62, s62, 0x4000
	s_cmp_ge_u32 s62, 0x14000
	s_cselect_b32 s69, 0x14000, 0
	s_sub_i32 s62, s62, s69
	v_add_u32_e32 v151, s62, v140
	v_cvt_pk_bf16_f32 v191, v90, v91
	v_cvt_pk_bf16_f32 v193, v94, v95
	s_add_i32 m0, s41, s63
	s_add_u32 s42, s46, 0x5d81000
	s_addc_u32 s43, s47, 0
	global_load_lds_dwordx4 v150, s[42:43]
	s_waitcnt lgkmcnt(10)
	v_mfma_f32_32x32x16_bf16 v[16:31], v[186:189], v[242:245], v[16:31]
	v_exp_f32_e32 v96, v96
	v_exp_f32_e32 v97, v97
	ds_read_b128 v[194:197], v149 offset:32768
	s_add_i32 m0, s71, s63
	s_add_u32 s42, s46, 0x5dc1000
	s_addc_u32 s43, s47, 0
	global_load_lds_dwordx4 v150, s[42:43]
	s_waitcnt lgkmcnt(9)
	v_mfma_f32_32x32x16_bf16 v[0:15], v[186:189], v[246:249], v[0:15]
	v_exp_f32_e32 v98, v98
	v_exp_f32_e32 v99, v99
	v_add_f32_e32 v234, v234, v96
	ds_read_b128 v[198:201], v148 offset:32768
	s_waitcnt lgkmcnt(8)
	v_mfma_f32_32x32x16_bf16 v[48:63], v[190:193], v[250:253], v[48:63]
	v_exp_f32_e32 v100, v100
	v_exp_f32_e32 v101, v101
	v_add_f32_e32 v235, v235, v97
	v_add_f32_e32 v234, v234, v98
	ds_read_b128 v[202:205], v143 offset:32768
	s_waitcnt lgkmcnt(7)
	v_mfma_f32_32x32x16_bf16 v[32:47], v[190:193], v[152:155], v[32:47]
	v_exp_f32_e32 v102, v102
	v_exp_f32_e32 v103, v103
	v_add_f32_e32 v235, v235, v99
	v_add_f32_e32 v234, v234, v100
	ds_read_b128 v[206:209], v141 offset:32768
	s_waitcnt lgkmcnt(6)
	v_mfma_f32_32x32x16_bf16 v[16:31], v[190:193], v[226:229], v[16:31]
	v_add_f32_e32 v235, v235, v101
	v_add_f32_e32 v234, v234, v102
	v_add_f32_e32 v235, v235, v103
	v_cvt_pk_bf16_f32 v178, v96, v97
	v_cvt_pk_bf16_f32 v180, v100, v101
	ds_read_b128 v[210:213], v149 offset:40960
	s_waitcnt lgkmcnt(5)
	v_mfma_f32_32x32x16_bf16 v[0:15], v[190:193], v[230:233], v[0:15]
	v_cvt_pk_bf16_f32 v179, v98, v99
	v_cvt_pk_bf16_f32 v181, v102, v103
	ds_read_b128 v[214:217], v148 offset:40960
	s_waitcnt lgkmcnt(5)
	v_mfma_f32_32x32x16_bf16 v[64:79], v[194:197], v[124:127], 0
	v_exp_f32_e32 v104, v104
	v_exp_f32_e32 v105, v105
	ds_read_b128 v[218:221], v143 offset:40960
	s_waitcnt lgkmcnt(5)
	v_mfma_f32_32x32x16_bf16 v[64:79], v[198:201], v[120:123], v[64:79]
	v_exp_f32_e32 v106, v106
	v_exp_f32_e32 v107, v107
	v_add_f32_e32 v234, v234, v104
	ds_read_b128 v[222:225], v141 offset:40960
	ds_read_b64_tr_b16 v[226:227], v151 offset:0
	ds_read_b64_tr_b16 v[228:229], v151 offset:2048
	s_waitcnt lgkmcnt(7)
	v_mfma_f32_32x32x16_bf16 v[64:79], v[202:205], v[116:119], v[64:79]
	v_exp_f32_e32 v108, v108
	v_exp_f32_e32 v109, v109
	v_add_f32_e32 v235, v235, v105
	v_add_f32_e32 v234, v234, v106
	ds_read_b64_tr_b16 v[230:231], v151 offset:512
	ds_read_b64_tr_b16 v[232:233], v151 offset:2560
	s_waitcnt lgkmcnt(8)
	v_mfma_f32_32x32x16_bf16 v[64:79], v[206:209], v[112:115], v[64:79]
	v_exp_f32_e32 v110, v110
	v_exp_f32_e32 v111, v111
	v_add_f32_e32 v235, v235, v107
	v_add_f32_e32 v234, v234, v108
	ds_read_b64_tr_b16 v[238:239], v151 offset:1024
	ds_read_b64_tr_b16 v[240:241], v151 offset:3072
	s_waitcnt lgkmcnt(9)
	v_mfma_f32_32x32x16_bf16 v[80:95], v[210:213], v[124:127], 0
	v_add_f32_e32 v235, v235, v109
	v_add_f32_e32 v234, v234, v110
	v_add_f32_e32 v235, v235, v111
	v_cvt_pk_bf16_f32 v182, v104, v105
	v_cvt_pk_bf16_f32 v184, v108, v109
	ds_read_b64_tr_b16 v[242:243], v151 offset:1536
	ds_read_b64_tr_b16 v[244:245], v151 offset:3584
	s_waitcnt lgkmcnt(10)
	v_mfma_f32_32x32x16_bf16 v[80:95], v[214:217], v[120:123], v[80:95]
	v_cvt_pk_bf16_f32 v183, v106, v107
	v_cvt_pk_bf16_f32 v185, v110, v111
	ds_read_b64_tr_b16 v[246:247], v151 offset:4096
	ds_read_b64_tr_b16 v[248:249], v151 offset:6144
	s_waitcnt lgkmcnt(11)
	v_mfma_f32_32x32x16_bf16 v[80:95], v[218:221], v[116:119], v[80:95]
	v_exp_f32_e32 v162, v162
	v_exp_f32_e32 v163, v163
	ds_read_b64_tr_b16 v[250:251], v151 offset:4608
	ds_read_b64_tr_b16 v[252:253], v151 offset:6656
	s_waitcnt lgkmcnt(12)
	v_mfma_f32_32x32x16_bf16 v[80:95], v[222:225], v[112:115], v[80:95]
	v_exp_f32_e32 v164, v164
	v_exp_f32_e32 v165, v165
	v_add_f32_e32 v234, v234, v162
	ds_read_b64_tr_b16 v[152:153], v151 offset:5120
	ds_read_b64_tr_b16 v[154:155], v151 offset:7168
	s_waitcnt lgkmcnt(12)
	v_mfma_f32_32x32x16_bf16 v[48:63], v[178:181], v[226:229], v[48:63]
	v_exp_f32_e32 v166, v166
	v_exp_f32_e32 v167, v167
	v_add_f32_e32 v235, v235, v163
	v_add_f32_e32 v234, v234, v164
	ds_read_b64_tr_b16 v[226:227], v151 offset:5632
	ds_read_b64_tr_b16 v[228:229], v151 offset:7680
	s_waitcnt lgkmcnt(12)
	v_mfma_f32_32x32x16_bf16 v[32:47], v[178:181], v[230:233], v[32:47]
	v_exp_f32_e32 v168, v168
	v_exp_f32_e32 v169, v169
	v_add_f32_e32 v235, v235, v165
	v_add_f32_e32 v234, v234, v166
	ds_read_b64_tr_b16 v[230:231], v151 offset:8192
	ds_read_b64_tr_b16 v[232:233], v151 offset:10240
	s_waitcnt lgkmcnt(12)
	v_mfma_f32_32x32x16_bf16 v[16:31], v[178:181], v[238:241], v[16:31]
	v_add_f32_e32 v235, v235, v167
	v_add_f32_e32 v234, v234, v168
	v_add_f32_e32 v235, v235, v169
	v_cvt_pk_bf16_f32 v186, v162, v163
	v_cvt_pk_bf16_f32 v188, v166, v167
	ds_read_b64_tr_b16 v[238:239], v151 offset:8704
	ds_read_b64_tr_b16 v[240:241], v151 offset:10752
	s_waitcnt lgkmcnt(12)
	v_mfma_f32_32x32x16_bf16 v[0:15], v[178:181], v[242:245], v[0:15]
	v_cvt_pk_bf16_f32 v187, v164, v165
	v_cvt_pk_bf16_f32 v189, v168, v169
	ds_read_b64_tr_b16 v[242:243], v151 offset:9216
	ds_read_b64_tr_b16 v[244:245], v151 offset:11264
	s_waitcnt lgkmcnt(12)
	v_mfma_f32_32x32x16_bf16 v[48:63], v[182:185], v[246:249], v[48:63]
	v_exp_f32_e32 v170, v170
	v_exp_f32_e32 v171, v171
	ds_read_b64_tr_b16 v[246:247], v151 offset:9728
	ds_read_b64_tr_b16 v[248:249], v151 offset:11776
	s_waitcnt lgkmcnt(12)
	v_mfma_f32_32x32x16_bf16 v[32:47], v[182:185], v[250:253], v[32:47]
	v_exp_f32_e32 v172, v172
	v_exp_f32_e32 v173, v173
	v_add_f32_e32 v234, v234, v170
	ds_read_b64_tr_b16 v[250:251], v151 offset:12288
	ds_read_b64_tr_b16 v[252:253], v151 offset:14336
	s_waitcnt lgkmcnt(12)
	v_mfma_f32_32x32x16_bf16 v[16:31], v[182:185], v[152:155], v[16:31]
	v_exp_f32_e32 v174, v174
	v_exp_f32_e32 v175, v175
	v_add_f32_e32 v235, v235, v171
	v_add_f32_e32 v234, v234, v172
	ds_read_b64_tr_b16 v[152:153], v151 offset:12800
	ds_read_b64_tr_b16 v[154:155], v151 offset:14848
	s_waitcnt lgkmcnt(12)
	v_mfma_f32_32x32x16_bf16 v[0:15], v[182:185], v[226:229], v[0:15]
	v_exp_f32_e32 v176, v176
	v_exp_f32_e32 v177, v177
	v_add_f32_e32 v235, v235, v173
	v_add_f32_e32 v234, v234, v174
	ds_read_b64_tr_b16 v[226:227], v151 offset:13312
	ds_read_b64_tr_b16 v[228:229], v151 offset:15360
	s_waitcnt lgkmcnt(12)
	v_mfma_f32_32x32x16_bf16 v[48:63], v[186:189], v[230:233], v[48:63]
	v_add_f32_e32 v235, v235, v175
	v_add_f32_e32 v234, v234, v176
	v_add_f32_e32 v235, v235, v177
	v_cvt_pk_bf16_f32 v190, v170, v171
	v_cvt_pk_bf16_f32 v192, v174, v175
	ds_read_b64_tr_b16 v[230:231], v151 offset:13824
	ds_read_b64_tr_b16 v[232:233], v151 offset:15872
	s_waitcnt lgkmcnt(12)
	v_mfma_f32_32x32x16_bf16 v[32:47], v[186:189], v[238:241], v[32:47]
	s_add_i32 s62, s62, 0x4000
	s_cmp_ge_u32 s62, 0x14000
	s_cselect_b32 s69, 0x14000, 0
	s_sub_i32 s62, s62, s69
	v_add_u32_e32 v151, s62, v140
	v_cvt_pk_bf16_f32 v191, v172, v173
	v_cvt_pk_bf16_f32 v193, v176, v177
	s_waitcnt lgkmcnt(10)
	v_mfma_f32_32x32x16_bf16 v[16:31], v[186:189], v[242:245], v[16:31]
	v_exp_f32_e32 v64, v64
	v_exp_f32_e32 v65, v65
	ds_read_b128 v[194:197], v149 offset:49152
	s_waitcnt lgkmcnt(9)
	v_mfma_f32_32x32x16_bf16 v[0:15], v[186:189], v[246:249], v[0:15]
	v_exp_f32_e32 v66, v66
	v_exp_f32_e32 v67, v67
	v_add_f32_e32 v234, v234, v64
	ds_read_b128 v[198:201], v148 offset:49152
	s_waitcnt lgkmcnt(8)
	v_mfma_f32_32x32x16_bf16 v[48:63], v[190:193], v[250:253], v[48:63]
	v_exp_f32_e32 v68, v68
	v_exp_f32_e32 v69, v69
	v_add_f32_e32 v235, v235, v65
	v_add_f32_e32 v234, v234, v66
	ds_read_b128 v[202:205], v143 offset:49152
	s_waitcnt lgkmcnt(7)
	v_mfma_f32_32x32x16_bf16 v[32:47], v[190:193], v[152:155], v[32:47]
	v_exp_f32_e32 v70, v70
	v_exp_f32_e32 v71, v71
	v_add_f32_e32 v235, v235, v67
	v_add_f32_e32 v234, v234, v68
	ds_read_b128 v[206:209], v141 offset:49152
	s_waitcnt lgkmcnt(6)
	v_mfma_f32_32x32x16_bf16 v[16:31], v[190:193], v[226:229], v[16:31]
	v_add_f32_e32 v235, v235, v69
	v_add_f32_e32 v234, v234, v70
	v_add_f32_e32 v235, v235, v71
	v_cvt_pk_bf16_f32 v178, v64, v65
	v_cvt_pk_bf16_f32 v180, v68, v69
	ds_read_b128 v[210:213], v149 offset:57344
	s_waitcnt lgkmcnt(5)
	v_mfma_f32_32x32x16_bf16 v[0:15], v[190:193], v[230:233], v[0:15]
	v_cvt_pk_bf16_f32 v179, v66, v67
	v_cvt_pk_bf16_f32 v181, v70, v71
	ds_read_b128 v[214:217], v148 offset:57344
	s_waitcnt lgkmcnt(5)
	v_mfma_f32_32x32x16_bf16 v[96:111], v[194:197], v[124:127], 0
	v_exp_f32_e32 v72, v72
	v_exp_f32_e32 v73, v73
	ds_read_b128 v[218:221], v143 offset:57344
	s_waitcnt lgkmcnt(5)
	v_mfma_f32_32x32x16_bf16 v[96:111], v[198:201], v[120:123], v[96:111]
	v_exp_f32_e32 v74, v74
	v_exp_f32_e32 v75, v75
	v_add_f32_e32 v234, v234, v72
	ds_read_b128 v[222:225], v141 offset:57344
	ds_read_b64_tr_b16 v[226:227], v151 offset:0
	ds_read_b64_tr_b16 v[228:229], v151 offset:2048
	s_waitcnt lgkmcnt(7)
	v_mfma_f32_32x32x16_bf16 v[96:111], v[202:205], v[116:119], v[96:111]
	v_exp_f32_e32 v76, v76
	v_exp_f32_e32 v77, v77
	v_add_f32_e32 v235, v235, v73
	v_add_f32_e32 v234, v234, v74
	ds_read_b64_tr_b16 v[230:231], v151 offset:512
	ds_read_b64_tr_b16 v[232:233], v151 offset:2560
	s_waitcnt lgkmcnt(8)
	v_mfma_f32_32x32x16_bf16 v[96:111], v[206:209], v[112:115], v[96:111]
	v_exp_f32_e32 v78, v78
	v_exp_f32_e32 v79, v79
	v_add_f32_e32 v235, v235, v75
	v_add_f32_e32 v234, v234, v76
	ds_read_b64_tr_b16 v[238:239], v151 offset:1024
	ds_read_b64_tr_b16 v[240:241], v151 offset:3072
	s_waitcnt lgkmcnt(9)
	v_mfma_f32_32x32x16_bf16 v[162:177], v[210:213], v[124:127], 0
	v_add_f32_e32 v235, v235, v77
	v_add_f32_e32 v234, v234, v78
	v_add_f32_e32 v235, v235, v79
	v_cvt_pk_bf16_f32 v182, v72, v73
	v_cvt_pk_bf16_f32 v184, v76, v77
	ds_read_b64_tr_b16 v[242:243], v151 offset:1536
	ds_read_b64_tr_b16 v[244:245], v151 offset:3584
	s_waitcnt lgkmcnt(10)
	v_mfma_f32_32x32x16_bf16 v[162:177], v[214:217], v[120:123], v[162:177]
	v_cvt_pk_bf16_f32 v183, v74, v75
	v_cvt_pk_bf16_f32 v185, v78, v79
	ds_read_b64_tr_b16 v[246:247], v151 offset:4096
	ds_read_b64_tr_b16 v[248:249], v151 offset:6144
	s_waitcnt lgkmcnt(11)
	v_mfma_f32_32x32x16_bf16 v[162:177], v[218:221], v[116:119], v[162:177]
	v_exp_f32_e32 v80, v80
	v_exp_f32_e32 v81, v81
	ds_read_b64_tr_b16 v[250:251], v151 offset:4608
	ds_read_b64_tr_b16 v[252:253], v151 offset:6656
	s_waitcnt lgkmcnt(12)
	v_mfma_f32_32x32x16_bf16 v[162:177], v[222:225], v[112:115], v[162:177]
	v_exp_f32_e32 v82, v82
	v_exp_f32_e32 v83, v83
	v_add_f32_e32 v234, v234, v80
	ds_read_b64_tr_b16 v[152:153], v151 offset:5120
	ds_read_b64_tr_b16 v[154:155], v151 offset:7168
	s_waitcnt lgkmcnt(12)
	v_mfma_f32_32x32x16_bf16 v[48:63], v[178:181], v[226:229], v[48:63]
	v_exp_f32_e32 v84, v84
	v_exp_f32_e32 v85, v85
	v_add_f32_e32 v235, v235, v81
	v_add_f32_e32 v234, v234, v82
	ds_read_b64_tr_b16 v[226:227], v151 offset:5632
	ds_read_b64_tr_b16 v[228:229], v151 offset:7680
	s_waitcnt lgkmcnt(12)
	v_mfma_f32_32x32x16_bf16 v[32:47], v[178:181], v[230:233], v[32:47]
	v_exp_f32_e32 v86, v86
	v_exp_f32_e32 v87, v87
	v_add_f32_e32 v235, v235, v83
	v_add_f32_e32 v234, v234, v84
	ds_read_b64_tr_b16 v[230:231], v151 offset:8192
	ds_read_b64_tr_b16 v[232:233], v151 offset:10240
	s_waitcnt lgkmcnt(12)
	v_mfma_f32_32x32x16_bf16 v[16:31], v[178:181], v[238:241], v[16:31]
	v_add_f32_e32 v235, v235, v85
	v_add_f32_e32 v234, v234, v86
	v_add_f32_e32 v235, v235, v87
	v_cvt_pk_bf16_f32 v186, v80, v81
	v_cvt_pk_bf16_f32 v188, v84, v85
	ds_read_b64_tr_b16 v[238:239], v151 offset:8704
	ds_read_b64_tr_b16 v[240:241], v151 offset:10752
	s_waitcnt lgkmcnt(12)
	v_mfma_f32_32x32x16_bf16 v[0:15], v[178:181], v[242:245], v[0:15]
	v_cvt_pk_bf16_f32 v187, v82, v83
	v_cvt_pk_bf16_f32 v189, v86, v87
	ds_read_b64_tr_b16 v[242:243], v151 offset:9216
	ds_read_b64_tr_b16 v[244:245], v151 offset:11264
	s_waitcnt lgkmcnt(12)
	v_mfma_f32_32x32x16_bf16 v[48:63], v[182:185], v[246:249], v[48:63]
	v_exp_f32_e32 v88, v88
	v_exp_f32_e32 v89, v89
	ds_read_b64_tr_b16 v[246:247], v151 offset:9728
	ds_read_b64_tr_b16 v[248:249], v151 offset:11776
	s_waitcnt lgkmcnt(12)
	v_mfma_f32_32x32x16_bf16 v[32:47], v[182:185], v[250:253], v[32:47]
	v_exp_f32_e32 v90, v90
	v_exp_f32_e32 v91, v91
	v_add_f32_e32 v234, v234, v88
	ds_read_b64_tr_b16 v[250:251], v151 offset:12288
	ds_read_b64_tr_b16 v[252:253], v151 offset:14336
	s_waitcnt lgkmcnt(12)
	v_mfma_f32_32x32x16_bf16 v[16:31], v[182:185], v[152:155], v[16:31]
	v_exp_f32_e32 v92, v92
	v_exp_f32_e32 v93, v93
	v_add_f32_e32 v235, v235, v89
	v_add_f32_e32 v234, v234, v90
	ds_read_b64_tr_b16 v[152:153], v151 offset:12800
	ds_read_b64_tr_b16 v[154:155], v151 offset:14848
	s_waitcnt lgkmcnt(12)
	v_mfma_f32_32x32x16_bf16 v[0:15], v[182:185], v[226:229], v[0:15]
	v_exp_f32_e32 v94, v94
	v_exp_f32_e32 v95, v95
	v_add_f32_e32 v235, v235, v91
	v_add_f32_e32 v234, v234, v92
	ds_read_b64_tr_b16 v[226:227], v151 offset:13312
	ds_read_b64_tr_b16 v[228:229], v151 offset:15360
	s_waitcnt lgkmcnt(12)
	v_mfma_f32_32x32x16_bf16 v[48:63], v[186:189], v[230:233], v[48:63]
	v_add_f32_e32 v235, v235, v93
	v_add_f32_e32 v234, v234, v94
	v_add_f32_e32 v235, v235, v95
	v_cvt_pk_bf16_f32 v190, v88, v89
	v_cvt_pk_bf16_f32 v192, v92, v93
	ds_read_b64_tr_b16 v[230:231], v151 offset:13824
	ds_read_b64_tr_b16 v[232:233], v151 offset:15872
	s_waitcnt lgkmcnt(12)
	v_mfma_f32_32x32x16_bf16 v[32:47], v[186:189], v[238:241], v[32:47]
	s_waitcnt vmcnt(0)
	s_barrier
	s_add_i32 s62, s62, 0x4000
	s_cmp_ge_u32 s62, 0x14000
	s_cselect_b32 s69, 0x14000, 0
	s_sub_i32 s62, s62, s69
	v_add_u32_e32 v151, s62, v140
	v_cvt_pk_bf16_f32 v191, v90, v91
	v_cvt_pk_bf16_f32 v193, v94, v95
	s_waitcnt lgkmcnt(10)
	v_mfma_f32_32x32x16_bf16 v[16:31], v[186:189], v[242:245], v[16:31]
	v_exp_f32_e32 v96, v96
	v_exp_f32_e32 v97, v97
	s_waitcnt lgkmcnt(8)
	v_mfma_f32_32x32x16_bf16 v[0:15], v[186:189], v[246:249], v[0:15]
	v_exp_f32_e32 v98, v98
	v_exp_f32_e32 v99, v99
	v_add_f32_e32 v234, v234, v96
	s_waitcnt lgkmcnt(6)
	v_mfma_f32_32x32x16_bf16 v[48:63], v[190:193], v[250:253], v[48:63]
	v_exp_f32_e32 v100, v100
	v_exp_f32_e32 v101, v101
	v_add_f32_e32 v235, v235, v97
	v_add_f32_e32 v234, v234, v98
	s_waitcnt lgkmcnt(4)
	v_mfma_f32_32x32x16_bf16 v[32:47], v[190:193], v[152:155], v[32:47]
	v_exp_f32_e32 v102, v102
	v_exp_f32_e32 v103, v103
	v_add_f32_e32 v235, v235, v99
	v_add_f32_e32 v234, v234, v100
	s_waitcnt lgkmcnt(2)
	v_mfma_f32_32x32x16_bf16 v[16:31], v[190:193], v[226:229], v[16:31]
	v_add_f32_e32 v235, v235, v101
	v_add_f32_e32 v234, v234, v102
	v_add_f32_e32 v235, v235, v103
	v_cvt_pk_bf16_f32 v178, v96, v97
	v_cvt_pk_bf16_f32 v180, v100, v101
	s_waitcnt lgkmcnt(0)
	v_mfma_f32_32x32x16_bf16 v[0:15], v[190:193], v[230:233], v[0:15]
	v_cvt_pk_bf16_f32 v179, v98, v99
	v_cvt_pk_bf16_f32 v181, v102, v103
	v_exp_f32_e32 v104, v104
	v_exp_f32_e32 v105, v105
	v_exp_f32_e32 v106, v106
	v_exp_f32_e32 v107, v107
	v_add_f32_e32 v234, v234, v104
	ds_read_b64_tr_b16 v[226:227], v151 offset:0
	ds_read_b64_tr_b16 v[228:229], v151 offset:2048
	v_exp_f32_e32 v108, v108
	v_exp_f32_e32 v109, v109
	v_add_f32_e32 v235, v235, v105
	v_add_f32_e32 v234, v234, v106
	ds_read_b64_tr_b16 v[230:231], v151 offset:512
	ds_read_b64_tr_b16 v[232:233], v151 offset:2560
	v_exp_f32_e32 v110, v110
	v_exp_f32_e32 v111, v111
	v_add_f32_e32 v235, v235, v107
	v_add_f32_e32 v234, v234, v108
	ds_read_b64_tr_b16 v[238:239], v151 offset:1024
	ds_read_b64_tr_b16 v[240:241], v151 offset:3072
	v_add_f32_e32 v235, v235, v109
	v_add_f32_e32 v234, v234, v110
	v_add_f32_e32 v235, v235, v111
	v_cvt_pk_bf16_f32 v182, v104, v105
	v_cvt_pk_bf16_f32 v184, v108, v109
	ds_read_b64_tr_b16 v[242:243], v151 offset:1536
	ds_read_b64_tr_b16 v[244:245], v151 offset:3584
	v_cvt_pk_bf16_f32 v183, v106, v107
	v_cvt_pk_bf16_f32 v185, v110, v111
	ds_read_b64_tr_b16 v[246:247], v151 offset:4096
	ds_read_b64_tr_b16 v[248:249], v151 offset:6144
	v_exp_f32_e32 v162, v162
	v_exp_f32_e32 v163, v163
	ds_read_b64_tr_b16 v[250:251], v151 offset:4608
	ds_read_b64_tr_b16 v[252:253], v151 offset:6656
	v_exp_f32_e32 v164, v164
	v_exp_f32_e32 v165, v165
	v_add_f32_e32 v234, v234, v162
	ds_read_b64_tr_b16 v[152:153], v151 offset:5120
	ds_read_b64_tr_b16 v[154:155], v151 offset:7168
	s_waitcnt lgkmcnt(12)
	v_mfma_f32_32x32x16_bf16 v[48:63], v[178:181], v[226:229], v[48:63]
	v_exp_f32_e32 v166, v166
	v_exp_f32_e32 v167, v167
	v_add_f32_e32 v235, v235, v163
	v_add_f32_e32 v234, v234, v164
	ds_read_b64_tr_b16 v[226:227], v151 offset:5632
	ds_read_b64_tr_b16 v[228:229], v151 offset:7680
	s_waitcnt lgkmcnt(12)
	v_mfma_f32_32x32x16_bf16 v[32:47], v[178:181], v[230:233], v[32:47]
	v_exp_f32_e32 v168, v168
	v_exp_f32_e32 v169, v169
	v_add_f32_e32 v235, v235, v165
	v_add_f32_e32 v234, v234, v166
	ds_read_b64_tr_b16 v[230:231], v151 offset:8192
	ds_read_b64_tr_b16 v[232:233], v151 offset:10240
	s_waitcnt lgkmcnt(12)
	v_mfma_f32_32x32x16_bf16 v[16:31], v[178:181], v[238:241], v[16:31]
	v_add_f32_e32 v235, v235, v167
	v_add_f32_e32 v234, v234, v168
	v_add_f32_e32 v235, v235, v169
	v_cvt_pk_bf16_f32 v186, v162, v163
	v_cvt_pk_bf16_f32 v188, v166, v167
	ds_read_b64_tr_b16 v[238:239], v151 offset:8704
	ds_read_b64_tr_b16 v[240:241], v151 offset:10752
	s_waitcnt lgkmcnt(12)
	v_mfma_f32_32x32x16_bf16 v[0:15], v[178:181], v[242:245], v[0:15]
	v_cvt_pk_bf16_f32 v187, v164, v165
	v_cvt_pk_bf16_f32 v189, v168, v169
	ds_read_b64_tr_b16 v[242:243], v151 offset:9216
	ds_read_b64_tr_b16 v[244:245], v151 offset:11264
	s_waitcnt lgkmcnt(12)
	v_mfma_f32_32x32x16_bf16 v[48:63], v[182:185], v[246:249], v[48:63]
	v_exp_f32_e32 v170, v170
	v_exp_f32_e32 v171, v171
	ds_read_b64_tr_b16 v[246:247], v151 offset:9728
	ds_read_b64_tr_b16 v[248:249], v151 offset:11776
	s_waitcnt lgkmcnt(12)
	v_mfma_f32_32x32x16_bf16 v[32:47], v[182:185], v[250:253], v[32:47]
	v_exp_f32_e32 v172, v172
	v_exp_f32_e32 v173, v173
	v_add_f32_e32 v234, v234, v170
	ds_read_b64_tr_b16 v[250:251], v151 offset:12288
	ds_read_b64_tr_b16 v[252:253], v151 offset:14336
	s_waitcnt lgkmcnt(12)
	v_mfma_f32_32x32x16_bf16 v[16:31], v[182:185], v[152:155], v[16:31]
	v_exp_f32_e32 v174, v174
	v_exp_f32_e32 v175, v175
	v_add_f32_e32 v235, v235, v171
	v_add_f32_e32 v234, v234, v172
	ds_read_b64_tr_b16 v[152:153], v151 offset:12800
	ds_read_b64_tr_b16 v[154:155], v151 offset:14848
	s_waitcnt lgkmcnt(12)
	v_mfma_f32_32x32x16_bf16 v[0:15], v[182:185], v[226:229], v[0:15]
	v_exp_f32_e32 v176, v176
	v_exp_f32_e32 v177, v177
	v_add_f32_e32 v235, v235, v173
	v_add_f32_e32 v234, v234, v174
	ds_read_b64_tr_b16 v[226:227], v151 offset:13312
	ds_read_b64_tr_b16 v[228:229], v151 offset:15360
	s_waitcnt lgkmcnt(12)
	v_mfma_f32_32x32x16_bf16 v[48:63], v[186:189], v[230:233], v[48:63]
	v_add_f32_e32 v235, v235, v175
	v_add_f32_e32 v234, v234, v176
	v_add_f32_e32 v235, v235, v177
	v_cvt_pk_bf16_f32 v190, v170, v171
	v_cvt_pk_bf16_f32 v192, v174, v175
	ds_read_b64_tr_b16 v[230:231], v151 offset:13824
	ds_read_b64_tr_b16 v[232:233], v151 offset:15872
	s_waitcnt lgkmcnt(12)
	v_mfma_f32_32x32x16_bf16 v[32:47], v[186:189], v[238:241], v[32:47]
	s_add_i32 s62, s62, 0x4000
	s_cmp_ge_u32 s62, 0x14000
	s_cselect_b32 s69, 0x14000, 0
	s_sub_i32 s62, s62, s69
	v_add_u32_e32 v151, s62, v140
	v_cvt_pk_bf16_f32 v191, v172, v173
	v_cvt_pk_bf16_f32 v193, v176, v177
	s_waitcnt lgkmcnt(10)
	v_mfma_f32_32x32x16_bf16 v[16:31], v[186:189], v[242:245], v[16:31]
	s_waitcnt lgkmcnt(8)
	v_mfma_f32_32x32x16_bf16 v[0:15], v[186:189], v[246:249], v[0:15]
	s_waitcnt lgkmcnt(6)
	v_mfma_f32_32x32x16_bf16 v[48:63], v[190:193], v[250:253], v[48:63]
	s_waitcnt lgkmcnt(4)
	v_mfma_f32_32x32x16_bf16 v[32:47], v[190:193], v[152:155], v[32:47]
	s_waitcnt lgkmcnt(2)
	v_mfma_f32_32x32x16_bf16 v[16:31], v[190:193], v[226:229], v[16:31]
	s_waitcnt lgkmcnt(0)
	v_mfma_f32_32x32x16_bf16 v[0:15], v[190:193], v[230:233], v[0:15]
	v_add_f32_e32 v68, v234, v235
	v_mov_b32_e32 v69, 0
	v_mov_b32_e32 v71, 0
	v_mov_b32_e32 v70, v68
	v_mov_b32_e32 v128, 0
	s_nop 0
	v_permlane32_swap_b32_e32 v68, v70
	s_and_b32 s4, s35, 0x3fffffc0
	s_lshl_b32 s4, s4, 2
	s_add_i32 s7, s4, 0
	s_add_i32 s7, s7, 0x24000
	s_setprio 0
	v_add_f32_e32 v64, v68, v70
	v_lshl_add_u32 v66, v136, 2, s7
	ds_write_b32 v66, v64
	global_load_dword v116, v129, s[14:15]
	v_lshlrev_b32_e32 v117, 2, v136
	global_load_dword v112, v117, s[58:59] offset:0
	global_load_dword v113, v117, s[58:59] offset:128
	global_load_dword v114, v117, s[58:59] offset:256
	global_load_dword v115, v117, s[58:59] offset:384
	s_lshl_b32 s4, s19, 4
	s_add_i32 s4, s18, s4
	s_lshl_b32 s5, s4, 13
	s_add_u32 s42, s65, s6
	s_addc_u32 s43, s20, 0
	s_add_u32 s42, s42, s5
	s_addc_u32 s43, s43, 0
	s_lshl_b32 s5, s4, 11
	s_add_u32 s46, s21, s6
	s_addc_u32 s47, s22, 0
	s_add_u32 s46, s46, s5
	s_addc_u32 s47, s47, 0
	v_lshlrev_b32_e32 v118, 1, v136
	v_lshl_add_u32 v119, v137, 13, v118
	v_lshl_add_u32 v118, v137, 15, v118
	global_load_ushort v162, v118, s[42:43] offset:0
	global_load_ushort v163, v118, s[42:43] offset:64
	global_load_ushort v164, v118, s[42:43] offset:128
	global_load_ushort v165, v118, s[42:43] offset:192
	s_add_u32 s42, s42, 0x2000
	s_addc_u32 s43, s43, 0
	global_load_ushort v166, v118, s[42:43] offset:0
	global_load_ushort v167, v118, s[42:43] offset:64
	global_load_ushort v168, v118, s[42:43] offset:128
	global_load_ushort v169, v118, s[42:43] offset:192
	s_add_u32 s42, s42, 0x2000
	s_addc_u32 s43, s43, 0
	global_load_ushort v170, v118, s[42:43] offset:0
	global_load_ushort v171, v118, s[42:43] offset:64
	global_load_ushort v172, v118, s[42:43] offset:128
	global_load_ushort v173, v118, s[42:43] offset:192
	s_add_u32 s42, s42, 0x2000
	s_addc_u32 s43, s43, 0
	global_load_ushort v174, v118, s[42:43] offset:0
	global_load_ushort v175, v118, s[42:43] offset:64
	global_load_ushort v176, v118, s[42:43] offset:128
	global_load_ushort v177, v118, s[42:43] offset:192
	s_add_u32 s42, s42, 0xa000
	s_addc_u32 s43, s43, 0
	global_load_ushort v178, v118, s[42:43] offset:0
	global_load_ushort v179, v118, s[42:43] offset:64
	global_load_ushort v180, v118, s[42:43] offset:128
	global_load_ushort v181, v118, s[42:43] offset:192
	s_add_u32 s42, s42, 0x2000
	s_addc_u32 s43, s43, 0
	global_load_ushort v182, v118, s[42:43] offset:0
	global_load_ushort v183, v118, s[42:43] offset:64
	global_load_ushort v184, v118, s[42:43] offset:128
	global_load_ushort v185, v118, s[42:43] offset:192
	s_add_u32 s42, s42, 0x2000
	s_addc_u32 s43, s43, 0
	global_load_ushort v186, v118, s[42:43] offset:0
	global_load_ushort v187, v118, s[42:43] offset:64
	global_load_ushort v188, v118, s[42:43] offset:128
	global_load_ushort v189, v118, s[42:43] offset:192
	s_add_u32 s42, s42, 0x2000
	s_addc_u32 s43, s43, 0
	global_load_ushort v190, v118, s[42:43] offset:0
	global_load_ushort v191, v118, s[42:43] offset:64
	global_load_ushort v192, v118, s[42:43] offset:128
	global_load_ushort v193, v118, s[42:43] offset:192
	v_add_u32_e32 v65, s7, v130
	s_waitcnt lgkmcnt(0)
	ds_read_b128 v[80:83], v65
	ds_read_b128 v[84:87], v65 offset:32
	ds_read_b128 v[88:91], v65 offset:64
	ds_read_b128 v[92:95], v65 offset:96
	s_waitcnt lgkmcnt(0)
	v_rcp_f32_e32 v96, v80
	v_rcp_f32_e32 v97, v81
	v_rcp_f32_e32 v98, v82
	v_rcp_f32_e32 v99, v83
	v_rcp_f32_e32 v100, v84
	v_rcp_f32_e32 v101, v85
	v_rcp_f32_e32 v102, v86
	v_rcp_f32_e32 v103, v87
	v_rcp_f32_e32 v104, v88
	v_rcp_f32_e32 v105, v89
	v_rcp_f32_e32 v106, v90
	v_rcp_f32_e32 v107, v91
	v_rcp_f32_e32 v108, v92
	v_rcp_f32_e32 v109, v93
	v_rcp_f32_e32 v110, v94
	v_rcp_f32_e32 v111, v95
	s_waitcnt vmcnt(36)
	v_readfirstlane_b32 s5, v116
	s_nop 3
	s_cmp_eq_u32 s19, 0
	s_cselect_b32 s5, 1.0, s5
	s_cselect_b32 s10, 1.0, -1.0
	s_cselect_b32 s40, 0, 0x2000
	s_cselect_b32 s41, 0x2000, 0
	v_mul_f32_e32 v96, s5, v96
	v_mul_f32_e32 v97, s5, v97
	v_mul_f32_e32 v98, s5, v98
	v_mul_f32_e32 v99, s5, v99
	v_mul_f32_e32 v100, s5, v100
	v_mul_f32_e32 v101, s5, v101
	v_mul_f32_e32 v102, s5, v102
	v_mul_f32_e32 v103, s5, v103
	v_mul_f32_e32 v104, s5, v104
	v_mul_f32_e32 v105, s5, v105
	v_mul_f32_e32 v106, s5, v106
	v_mul_f32_e32 v107, s5, v107
	v_mul_f32_e32 v108, s5, v108
	v_mul_f32_e32 v109, s5, v109
	v_mul_f32_e32 v110, s5, v110
	v_mul_f32_e32 v111, s5, v111
	s_waitcnt vmcnt(32)
	v_mov_b32_e32 v120, 0x3f4ccccd
	v_mul_f32_e32 v120, s10, v120
	v_mul_f32_e32 v112, v120, v112
	v_mul_f32_e32 v113, v120, v113
	v_mul_f32_e32 v114, v120, v114
	v_mul_f32_e32 v115, v120, v115
	s_barrier
	s_lshl_b32 s11, s34, 14
	v_lshl_add_u32 v121, v137, 11, v117
	v_add_u32_e32 v121, s11, v121
	s_add_i32 s62, s40, 0x0
	v_add_u32_e32 v140, s62, v121
	s_add_i32 s62, s41, 0x0
	v_add_u32_e32 v122, s62, v121
	s_add_i32 s62, s40, 0x400
	v_add_u32_e32 v141, s62, v121
	s_add_i32 s62, s41, 0x400
	v_add_u32_e32 v123, s62, v121
	s_add_i32 s62, s40, 0x1000
	v_add_u32_e32 v142, s62, v121
	s_add_i32 s62, s41, 0x1000
	v_add_u32_e32 v124, s62, v121
	s_add_i32 s62, s40, 0x1400
	v_add_u32_e32 v143, s62, v121
	s_add_i32 s62, s41, 0x1400
	v_add_u32_e32 v125, s62, v121
	s_cmp_eq_u32 s19, 0
	s_cbranch_scc0 .Lde_c1
	v_mul_f32_e32 v194, v48, v96
	v_mul_f32_e32 v202, v32, v96
	v_mul_f32_e32 v210, v16, v96
	v_mul_f32_e32 v218, v0, v96
	v_mul_f32_e32 v195, v49, v97
	v_mul_f32_e32 v203, v33, v97
	v_mul_f32_e32 v211, v17, v97
	v_mul_f32_e32 v219, v1, v97
	v_mul_f32_e32 v196, v50, v98
	v_mul_f32_e32 v204, v34, v98
	v_mul_f32_e32 v212, v18, v98
	v_mul_f32_e32 v220, v2, v98
	v_mul_f32_e32 v197, v51, v99
	v_mul_f32_e32 v205, v35, v99
	v_mul_f32_e32 v213, v19, v99
	v_mul_f32_e32 v221, v3, v99
	v_mul_f32_e32 v198, v52, v100
	v_mul_f32_e32 v206, v36, v100
	v_mul_f32_e32 v214, v20, v100
	v_mul_f32_e32 v222, v4, v100
	v_mul_f32_e32 v199, v53, v101
	v_mul_f32_e32 v207, v37, v101
	v_mul_f32_e32 v215, v21, v101
	v_mul_f32_e32 v223, v5, v101
	v_mul_f32_e32 v200, v54, v102
	v_mul_f32_e32 v208, v38, v102
	v_mul_f32_e32 v216, v22, v102
	v_mul_f32_e32 v224, v6, v102
	v_mul_f32_e32 v201, v55, v103
	v_mul_f32_e32 v209, v39, v103
	v_mul_f32_e32 v217, v23, v103
	v_mul_f32_e32 v225, v7, v103
	v_mul_f32_e32 v226, v56, v104
	v_mul_f32_e32 v227, v40, v104
	ds_write2_b32 v122, v226, v227 offset0:0 offset1:32
	v_mul_f32_e32 v228, v24, v104
	v_mul_f32_e32 v229, v8, v104
	ds_write2_b32 v122, v228, v229 offset0:64 offset1:96
	v_mul_f32_e32 v230, v57, v105
	v_mul_f32_e32 v231, v41, v105
	ds_write2_b32 v122, v230, v231 offset0:128 offset1:160
	v_mul_f32_e32 v232, v25, v105
	v_mul_f32_e32 v233, v9, v105
	ds_write2_b32 v122, v232, v233 offset0:192 offset1:224
	v_mul_f32_e32 v238, v58, v106
	v_mul_f32_e32 v239, v42, v106
	ds_write2_b32 v123, v238, v239 offset0:0 offset1:32
	v_mul_f32_e32 v240, v26, v106
	v_mul_f32_e32 v241, v10, v106
	ds_write2_b32 v123, v240, v241 offset0:64 offset1:96
	v_mul_f32_e32 v242, v59, v107
	v_mul_f32_e32 v243, v43, v107
	ds_write2_b32 v123, v242, v243 offset0:128 offset1:160
	v_mul_f32_e32 v244, v27, v107
	v_mul_f32_e32 v245, v11, v107
	ds_write2_b32 v123, v244, v245 offset0:192 offset1:224
	v_mul_f32_e32 v246, v60, v108
	v_mul_f32_e32 v247, v44, v108
	ds_write2_b32 v124, v246, v247 offset0:0 offset1:32
	v_mul_f32_e32 v248, v28, v108
	v_mul_f32_e32 v249, v12, v108
	ds_write2_b32 v124, v248, v249 offset0:64 offset1:96
	v_mul_f32_e32 v250, v61, v109
	v_mul_f32_e32 v251, v45, v109
	ds_write2_b32 v124, v250, v251 offset0:128 offset1:160
	v_mul_f32_e32 v252, v29, v109
	v_mul_f32_e32 v253, v13, v109
	ds_write2_b32 v124, v252, v253 offset0:192 offset1:224
	v_mul_f32_e32 v254, v62, v110
	v_mul_f32_e32 v255, v46, v110
	ds_write2_b32 v125, v254, v255 offset0:0 offset1:32
	v_mul_f32_e32 v146, v30, v110
	v_mul_f32_e32 v147, v14, v110
	ds_write2_b32 v125, v146, v147 offset0:64 offset1:96
	v_mul_f32_e32 v148, v63, v111
	v_mul_f32_e32 v149, v47, v111
	ds_write2_b32 v125, v148, v149 offset0:128 offset1:160
	v_mul_f32_e32 v150, v31, v111
	v_mul_f32_e32 v151, v15, v111
	ds_write2_b32 v125, v150, v151 offset0:192 offset1:224
	s_branch .Lde_join

.LBB0_390:
	s_lshl_b32 s34, s15, 8
	v_mov_b32 v128, 0
	s_add_i32 s82, s57, s34
	v_lshlrev_b32_e32 v154, 3, v132
	v_or_b32_e32 v128, s2, v154
	s_ashr_i32 s2, s82, 13
	s_mul_i32 s34, s2, 0xc00
	s_ashr_i32 s35, s34, 31
	s_ashr_i32 s83, s82, 31
	s_lshl_b64 s[34:35], s[34:35], 2
	v_or_b32_e32 v136, s58, v128
	s_add_u32 s58, s28, s34
	v_or_b32_e32 v140, s82, v152
	s_addc_u32 s59, s29, s35
	v_ashrrev_i32_e32 v141, 31, v140
	v_lshl_add_u64 v[128:129], v[136:137], 2, s[58:59]
	v_lshlrev_b64 v[130:131], 10, v[140:141]
	s_movk_i32 s2, 0x2000
	v_lshl_add_u64 v[130:131], v[130:131], 0, v[136:137]
	v_add_co_u32_e32 v146, vcc, s2, v128
	v_lshlrev_b64 v[148:149], 2, v[130:131]
	s_nop 0
	v_addc_co_u32_e32 v147, vcc, 0, v129, vcc
	v_lshl_add_u64 v[142:143], v[128:129], 0, s[6:7]
	v_lshl_add_u64 v[138:139], s[36:37], 0, v[148:149]
	global_load_dwordx4 v[128:131], v[146:147], off
	global_load_dwordx4 v[132:135], v[138:139], off offset:16
	global_load_dwordx4 v[162:165], v[138:139], off
	global_load_dwordx4 v[166:169], v[142:143], off offset:16
	v_readlane_b32 s48, v237, 1
	v_readlane_b32 s62, v237, 15
	v_readlane_b32 s63, v237, 16
	v_readlane_b32 s56, v237, 9
	v_readlane_b32 s57, v237, 10
	v_lshl_add_u64 v[148:149], s[62:63], 0, v[148:149]
	v_cmp_gt_u32_e32 vcc, 32, v153
	v_readlane_b32 s49, v237, 2
	v_readlane_b32 s50, v237, 3
	v_readlane_b32 s51, v237, 4
	v_readlane_b32 s52, v237, 5
	v_readlane_b32 s53, v237, 6
	v_readlane_b32 s54, v237, 7
	v_readlane_b32 s55, v237, 8
	v_readlane_b32 s58, v237, 11
	v_readlane_b32 s59, v237, 12
	v_readlane_b32 s60, v237, 13
	v_readlane_b32 s61, v237, 14
	s_waitcnt vmcnt(0)
	v_pk_fma_f32 v[128:129], v[112:113], v[128:129], v[162:163]
	v_pk_fma_f32 v[130:131], v[114:115], v[130:131], v[164:165]
	v_pk_fma_f32 v[132:133], v[120:121], v[166:167], v[132:133]
	v_pk_fma_f32 v[134:135], v[122:123], v[168:169], v[134:135]
	global_load_dwordx4 v[112:115], v[142:143], off offset:80
	global_load_dwordx4 v[120:123], v[142:143], off offset:64
	global_load_dwordx4 v[162:165], v[138:139], off offset:64
	global_load_dwordx4 v[166:169], v[138:139], off offset:80
	global_store_dwordx4 v[148:149], v[128:131], off
	global_store_dwordx4 v[148:149], v[132:135], off offset:16
	s_waitcnt vmcnt(3)
	v_pk_fma_f32 v[120:121], v[116:117], v[120:121], v[162:163]
	s_waitcnt vmcnt(2)
	v_pk_fma_f32 v[124:125], v[124:125], v[112:113], v[166:167]
	v_pk_fma_f32 v[122:123], v[118:119], v[122:123], v[164:165]
	v_pk_fma_f32 v[126:127], v[126:127], v[114:115], v[168:169]
	global_load_dwordx4 v[116:119], v[142:143], off offset:144
	global_load_dwordx4 v[112:115], v[142:143], off offset:128
	global_load_dwordx4 v[162:165], v[138:139], off offset:128
	global_load_dwordx4 v[166:169], v[138:139], off offset:144
	global_store_dwordx4 v[148:149], v[120:123], off offset:64
	global_store_dwordx4 v[148:149], v[124:127], off offset:80
	s_waitcnt vmcnt(3)
	v_pk_fma_f32 v[112:113], v[96:97], v[112:113], v[162:163]
	v_pk_fma_f32 v[114:115], v[98:99], v[114:115], v[164:165]
	s_waitcnt vmcnt(2)
	v_pk_fma_f32 v[116:117], v[104:105], v[116:117], v[166:167]
	v_pk_fma_f32 v[118:119], v[106:107], v[118:119], v[168:169]
	global_load_dwordx4 v[96:99], v[142:143], off offset:208
	global_load_dwordx4 v[104:107], v[142:143], off offset:192
	global_load_dwordx4 v[162:165], v[138:139], off offset:192
	global_load_dwordx4 v[166:169], v[138:139], off offset:208
	global_store_dwordx4 v[148:149], v[112:115], off offset:128
	global_store_dwordx4 v[148:149], v[116:119], off offset:144
	s_waitcnt vmcnt(3)
	v_pk_fma_f32 v[104:105], v[100:101], v[104:105], v[162:163]
	s_waitcnt vmcnt(2)
	v_pk_fma_f32 v[108:109], v[108:109], v[96:97], v[166:167]
	v_pk_fma_f32 v[106:107], v[102:103], v[106:107], v[164:165]
	v_pk_fma_f32 v[110:111], v[110:111], v[98:99], v[168:169]
	global_load_dwordx4 v[100:103], v[142:143], off offset:272
	global_load_dwordx4 v[96:99], v[142:143], off offset:256
	global_load_dwordx4 v[162:165], v[138:139], off offset:256
	global_load_dwordx4 v[166:169], v[138:139], off offset:272
	global_store_dwordx4 v[148:149], v[104:107], off offset:192
	global_store_dwordx4 v[148:149], v[108:111], off offset:208
	s_waitcnt vmcnt(3)
	v_pk_fma_f32 v[96:97], v[80:81], v[96:97], v[162:163]
	v_pk_fma_f32 v[98:99], v[82:83], v[98:99], v[164:165]
	s_waitcnt vmcnt(2)
	v_pk_fma_f32 v[100:101], v[88:89], v[100:101], v[166:167]
	v_pk_fma_f32 v[102:103], v[90:91], v[102:103], v[168:169]
	global_load_dwordx4 v[80:83], v[142:143], off offset:336
	global_load_dwordx4 v[88:91], v[142:143], off offset:320
	global_load_dwordx4 v[162:165], v[138:139], off offset:320
	global_load_dwordx4 v[166:169], v[138:139], off offset:336
	global_store_dwordx4 v[148:149], v[96:99], off offset:256
	global_store_dwordx4 v[148:149], v[100:103], off offset:272
	s_waitcnt vmcnt(3)
	v_pk_fma_f32 v[88:89], v[84:85], v[88:89], v[162:163]
	s_waitcnt vmcnt(2)
	v_pk_fma_f32 v[92:93], v[92:93], v[80:81], v[166:167]
	v_pk_fma_f32 v[90:91], v[86:87], v[90:91], v[164:165]
	v_pk_fma_f32 v[94:95], v[94:95], v[82:83], v[168:169]
	global_load_dwordx4 v[84:87], v[142:143], off offset:400
	global_load_dwordx4 v[80:83], v[142:143], off offset:384
	global_load_dwordx4 v[162:165], v[138:139], off offset:384
	global_load_dwordx4 v[166:169], v[138:139], off offset:400
	global_store_dwordx4 v[148:149], v[88:91], off offset:320
	global_store_dwordx4 v[148:149], v[92:95], off offset:336
	s_waitcnt vmcnt(3)
	v_pk_fma_f32 v[80:81], v[64:65], v[80:81], v[162:163]
	v_pk_fma_f32 v[82:83], v[66:67], v[82:83], v[164:165]
	s_waitcnt vmcnt(2)
	v_pk_fma_f32 v[84:85], v[72:73], v[84:85], v[166:167]
	v_pk_fma_f32 v[86:87], v[74:75], v[86:87], v[168:169]
	global_load_dwordx4 v[64:67], v[142:143], off offset:464
	global_load_dwordx4 v[72:75], v[142:143], off offset:448
	global_load_dwordx4 v[162:165], v[138:139], off offset:448
	global_load_dwordx4 v[166:169], v[138:139], off offset:464
	global_store_dwordx4 v[148:149], v[80:83], off offset:384
	global_store_dwordx4 v[148:149], v[84:87], off offset:400
	s_waitcnt vmcnt(3)
	v_pk_fma_f32 v[72:73], v[68:69], v[72:73], v[162:163]
	s_waitcnt vmcnt(2)
	v_pk_fma_f32 v[76:77], v[76:77], v[64:65], v[166:167]
	v_pk_fma_f32 v[74:75], v[70:71], v[74:75], v[164:165]
	v_pk_fma_f32 v[78:79], v[78:79], v[66:67], v[168:169]
	global_store_dwordx4 v[148:149], v[72:75], off offset:448
	global_store_dwordx4 v[148:149], v[76:79], off offset:464
	v_or_b32_e32 v138, 32, v140
	v_ashrrev_i32_e32 v139, 31, v138
	v_lshlrev_b64 v[64:65], 10, v[138:139]
	v_lshl_add_u64 v[64:65], v[64:65], 0, v[136:137]
	v_lshlrev_b64 v[148:149], 2, v[64:65]
	v_lshl_add_u64 v[170:171], s[36:37], 0, v[148:149]
	global_load_dwordx4 v[68:71], v[170:171], off offset:16
	global_load_dwordx4 v[64:67], v[170:171], off
	global_load_dwordx4 v[162:165], v[146:147], off
	global_load_dwordx4 v[166:169], v[142:143], off offset:16
	v_lshl_add_u64 v[146:147], s[62:63], 0, v[148:149]
	s_waitcnt vmcnt(1)
	v_pk_fma_f32 v[64:65], v[48:49], v[162:163], v[64:65]
	v_pk_fma_f32 v[66:67], v[50:51], v[164:165], v[66:67]
	s_waitcnt vmcnt(0)
	v_pk_fma_f32 v[68:69], v[56:57], v[166:167], v[68:69]
	v_pk_fma_f32 v[70:71], v[58:59], v[168:169], v[70:71]
	global_load_dwordx4 v[48:51], v[142:143], off offset:80
	global_load_dwordx4 v[56:59], v[142:143], off offset:64
	global_load_dwordx4 v[162:165], v[170:171], off offset:64
	global_load_dwordx4 v[166:169], v[170:171], off offset:80
	global_store_dwordx4 v[146:147], v[64:67], off
	global_store_dwordx4 v[146:147], v[68:71], off offset:16
	s_waitcnt vmcnt(3)
	v_pk_fma_f32 v[56:57], v[52:53], v[56:57], v[162:163]
	s_waitcnt vmcnt(2)
	v_pk_fma_f32 v[60:61], v[60:61], v[48:49], v[166:167]
	v_pk_fma_f32 v[58:59], v[54:55], v[58:59], v[164:165]
	v_pk_fma_f32 v[62:63], v[62:63], v[50:51], v[168:169]
	global_load_dwordx4 v[52:55], v[142:143], off offset:144
	global_load_dwordx4 v[48:51], v[142:143], off offset:128
	global_load_dwordx4 v[162:165], v[170:171], off offset:128
	global_load_dwordx4 v[166:169], v[170:171], off offset:144
	global_store_dwordx4 v[146:147], v[56:59], off offset:64
	global_store_dwordx4 v[146:147], v[60:63], off offset:80
	s_waitcnt vmcnt(3)
	v_pk_fma_f32 v[48:49], v[32:33], v[48:49], v[162:163]
	v_pk_fma_f32 v[50:51], v[34:35], v[50:51], v[164:165]
	s_waitcnt vmcnt(2)
	v_pk_fma_f32 v[52:53], v[40:41], v[52:53], v[166:167]
	v_pk_fma_f32 v[54:55], v[42:43], v[54:55], v[168:169]
	global_load_dwordx4 v[32:35], v[142:143], off offset:208
	global_load_dwordx4 v[40:43], v[142:143], off offset:192
	global_load_dwordx4 v[162:165], v[170:171], off offset:192
	global_load_dwordx4 v[166:169], v[170:171], off offset:208
	global_store_dwordx4 v[146:147], v[48:51], off offset:128
	global_store_dwordx4 v[146:147], v[52:55], off offset:144
	s_waitcnt vmcnt(3)
	v_pk_fma_f32 v[40:41], v[36:37], v[40:41], v[162:163]
	s_waitcnt vmcnt(2)
	v_pk_fma_f32 v[44:45], v[44:45], v[32:33], v[166:167]
	v_pk_fma_f32 v[42:43], v[38:39], v[42:43], v[164:165]
	v_pk_fma_f32 v[46:47], v[46:47], v[34:35], v[168:169]
	global_load_dwordx4 v[36:39], v[142:143], off offset:272
	global_load_dwordx4 v[32:35], v[142:143], off offset:256
	global_load_dwordx4 v[162:165], v[170:171], off offset:256
	global_load_dwordx4 v[166:169], v[170:171], off offset:272
	global_store_dwordx4 v[146:147], v[40:43], off offset:192
	global_store_dwordx4 v[146:147], v[44:47], off offset:208
	s_waitcnt vmcnt(3)
	v_pk_fma_f32 v[32:33], v[16:17], v[32:33], v[162:163]
	v_pk_fma_f32 v[34:35], v[18:19], v[34:35], v[164:165]
	s_waitcnt vmcnt(2)
	v_pk_fma_f32 v[36:37], v[24:25], v[36:37], v[166:167]
	v_pk_fma_f32 v[38:39], v[26:27], v[38:39], v[168:169]
	global_load_dwordx4 v[16:19], v[142:143], off offset:336
	global_load_dwordx4 v[24:27], v[142:143], off offset:320
	global_load_dwordx4 v[162:165], v[170:171], off offset:320
	global_load_dwordx4 v[166:169], v[170:171], off offset:336
	global_store_dwordx4 v[146:147], v[32:35], off offset:256
	global_store_dwordx4 v[146:147], v[36:39], off offset:272
	s_waitcnt vmcnt(3)
	v_pk_fma_f32 v[20:21], v[20:21], v[24:25], v[162:163]
	s_waitcnt vmcnt(2)
	v_pk_fma_f32 v[24:25], v[28:29], v[16:17], v[166:167]
	v_pk_fma_f32 v[22:23], v[22:23], v[26:27], v[164:165]
	v_pk_fma_f32 v[26:27], v[30:31], v[18:19], v[168:169]
	global_load_dwordx4 v[28:31], v[142:143], off offset:400
	global_load_dwordx4 v[16:19], v[142:143], off offset:384
	global_load_dwordx4 v[162:165], v[170:171], off offset:384
	global_load_dwordx4 v[166:169], v[170:171], off offset:400
	global_store_dwordx4 v[146:147], v[20:23], off offset:320
	global_store_dwordx4 v[146:147], v[24:27], off offset:336
	s_waitcnt vmcnt(3)
	v_pk_fma_f32 v[16:17], v[0:1], v[16:17], v[162:163]
	v_pk_fma_f32 v[18:19], v[2:3], v[18:19], v[164:165]
	s_waitcnt vmcnt(2)
	v_pk_fma_f32 v[8:9], v[8:9], v[28:29], v[166:167]
	v_pk_fma_f32 v[10:11], v[10:11], v[30:31], v[168:169]
	global_load_dwordx4 v[28:31], v[142:143], off offset:464
	global_load_dwordx4 v[0:3], v[142:143], off offset:448
	global_load_dwordx4 v[162:165], v[170:171], off offset:448
	global_load_dwordx4 v[166:169], v[170:171], off offset:464
	global_store_dwordx4 v[146:147], v[16:19], off offset:384
	global_store_dwordx4 v[146:147], v[8:11], off offset:400
	s_waitcnt vmcnt(3)
	v_pk_fma_f32 v[0:1], v[4:5], v[0:1], v[162:163]
	s_waitcnt vmcnt(2)
	v_pk_fma_f32 v[4:5], v[12:13], v[28:29], v[166:167]
	v_pk_fma_f32 v[2:3], v[6:7], v[2:3], v[164:165]
	v_pk_fma_f32 v[6:7], v[14:15], v[30:31], v[168:169]
	global_store_dwordx4 v[146:147], v[0:3], off offset:448
	global_store_dwordx4 v[146:147], v[4:7], off offset:464
	v_pk_mul_f32 v[12:13], v[128:129], v[128:129]
	v_pk_mul_f32 v[14:15], v[130:131], v[130:131]
	v_add_f32_e32 v12, v12, v13
	v_add_f32_e32 v12, v14, v12
	v_pk_mul_f32 v[28:29], v[120:121], v[120:121]
	v_add_f32_e32 v12, v15, v12
	v_add_f32_e32 v12, v12, v28
	v_pk_mul_f32 v[30:31], v[122:123], v[122:123]
	v_add_f32_e32 v12, v29, v12
	v_add_f32_e32 v12, v30, v12
	v_pk_mul_f32 v[142:143], v[132:133], v[132:133]
	v_add_f32_e32 v12, v31, v12
	v_add_f32_e32 v12, v142, v12
	v_pk_mul_f32 v[146:147], v[134:135], v[134:135]
	v_add_f32_e32 v12, v143, v12
	v_add_f32_e32 v12, v146, v12
	v_pk_mul_f32 v[148:149], v[124:125], v[124:125]
	v_add_f32_e32 v12, v147, v12
	v_add_f32_e32 v12, v148, v12
	v_pk_mul_f32 v[162:163], v[126:127], v[126:127]
	v_add_f32_e32 v12, v149, v12
	v_add_f32_e32 v12, v162, v12
	v_pk_mul_f32 v[164:165], v[112:113], v[112:113]
	v_add_f32_e32 v12, v163, v12
	v_add_f32_e32 v12, v164, v12
	v_pk_mul_f32 v[166:167], v[114:115], v[114:115]
	v_add_f32_e32 v12, v165, v12
	v_add_f32_e32 v12, v166, v12
	v_pk_mul_f32 v[168:169], v[104:105], v[104:105]
	v_add_f32_e32 v12, v167, v12
	v_add_f32_e32 v12, v168, v12
	v_pk_mul_f32 v[170:171], v[106:107], v[106:107]
	v_add_f32_e32 v12, v169, v12
	v_add_f32_e32 v12, v170, v12
	v_pk_mul_f32 v[172:173], v[116:117], v[116:117]
	v_add_f32_e32 v12, v171, v12
	v_add_f32_e32 v12, v172, v12
	v_pk_mul_f32 v[174:175], v[118:119], v[118:119]
	v_add_f32_e32 v12, v173, v12
	v_add_f32_e32 v12, v174, v12
	v_pk_mul_f32 v[176:177], v[108:109], v[108:109]
	v_add_f32_e32 v12, v175, v12
	v_add_f32_e32 v12, v176, v12
	v_pk_mul_f32 v[178:179], v[110:111], v[110:111]
	v_add_f32_e32 v12, v177, v12
	v_add_f32_e32 v12, v178, v12
	v_pk_mul_f32 v[180:181], v[96:97], v[96:97]
	v_add_f32_e32 v12, v179, v12
	v_add_f32_e32 v12, v180, v12
	v_pk_mul_f32 v[182:183], v[98:99], v[98:99]
	v_add_f32_e32 v12, v181, v12
	v_add_f32_e32 v12, v182, v12
	v_pk_mul_f32 v[184:185], v[88:89], v[88:89]
	v_add_f32_e32 v12, v183, v12
	v_add_f32_e32 v12, v184, v12
	v_pk_mul_f32 v[186:187], v[90:91], v[90:91]
	v_add_f32_e32 v12, v185, v12
	v_add_f32_e32 v12, v186, v12
	v_pk_mul_f32 v[188:189], v[100:101], v[100:101]
	v_add_f32_e32 v12, v187, v12
	v_add_f32_e32 v12, v188, v12
	v_pk_mul_f32 v[190:191], v[102:103], v[102:103]
	v_add_f32_e32 v12, v189, v12
	v_add_f32_e32 v12, v190, v12
	v_pk_mul_f32 v[192:193], v[92:93], v[92:93]
	v_add_f32_e32 v12, v191, v12
	v_add_f32_e32 v12, v192, v12
	v_pk_mul_f32 v[194:195], v[94:95], v[94:95]
	v_add_f32_e32 v12, v193, v12
	v_add_f32_e32 v12, v194, v12
	v_pk_mul_f32 v[196:197], v[80:81], v[80:81]
	v_add_f32_e32 v12, v195, v12
	v_add_f32_e32 v12, v196, v12
	v_pk_mul_f32 v[198:199], v[82:83], v[82:83]
	v_add_f32_e32 v12, v197, v12
	v_add_f32_e32 v12, v198, v12
	v_pk_mul_f32 v[200:201], v[72:73], v[72:73]
	v_add_f32_e32 v12, v199, v12
	v_add_f32_e32 v12, v200, v12
	v_pk_mul_f32 v[202:203], v[74:75], v[74:75]
	v_add_f32_e32 v12, v201, v12
	v_add_f32_e32 v12, v202, v12
	v_pk_mul_f32 v[204:205], v[84:85], v[84:85]
	v_add_f32_e32 v12, v203, v12
	v_add_f32_e32 v12, v204, v12
	v_pk_mul_f32 v[206:207], v[86:87], v[86:87]
	v_add_f32_e32 v12, v205, v12
	v_add_f32_e32 v12, v206, v12
	v_pk_mul_f32 v[208:209], v[76:77], v[76:77]
	v_add_f32_e32 v12, v207, v12
	v_add_f32_e32 v12, v208, v12
	v_pk_mul_f32 v[210:211], v[78:79], v[78:79]
	v_add_f32_e32 v12, v209, v12
	v_add_f32_e32 v12, v210, v12
	v_add_f32_e32 v14, v211, v12
	ds_bpermute_b32 v15, v145, v14
	s_lshl_b64 s[56:57], s[82:83], 2
	s_add_u32 s56, s0, s56
	s_addc_u32 s57, s1, s57
	v_lshlrev_b32_e32 v12, 2, v152
	v_mov_b32_e32 v13, v137
	v_lshl_add_u64 v[12:13], s[56:57], 0, v[12:13]
	s_and_saveexec_b64 s[56:57], vcc
	s_cbranch_execz .LBB0_392
	s_waitcnt lgkmcnt(0)
	v_add_f32_e32 v14, v14, v15
	global_atomic_add_f32 v[12:13], v14, off
